# batch-closed rmsnorm rows + NSA items; 11 of 20 grid barriers replaced by 64-workgroup XCC-local barriers (runtime-checked placement)
# speedup vs baseline: 1.0619x; 1.0297x over previous
; __device__ __forceinline__ int otid() { int t = threadIdx.x; asm volatile("" : "+v"(t)); return t; }
; template <int MODE>
; __device__ void phase_rmsnorm(const float* src, const float* __restrict__ w, u16* __restrict__ dstb, float* dstf) {
;   const int tid_ = otid();
;   const int lane = tid_ & 63;
;   const int gw = blockIdx.x * 4 + (tid_ >> 6);
;   const int nw = gridDim.x * 4;
;   float4 ww[4];
; #pragma unroll
;   for (int i = 0; i < 4; ++i) ww[i] = *(const float4*)(w + (i * 64 + lane) * 4);
;   float4 v[4], nv[4];
;   int row = gw;
;   if (row < TOK) {
; #pragma unroll
;     for (int i = 0; i < 4; ++i) v[i] = *(const float4*)(src + (size_t)row * DM + (i * 64 + lane) * 4);
;   }
;   while (row < TOK) {
;     const int nrow = row + nw;
;     if (nrow < TOK) {
; #pragma unroll
;       for (int i = 0; i < 4; ++i) nv[i] = *(const float4*)(src + (size_t)nrow * DM + (i * 64 + lane) * 4);
;     }
;     float ss = 0.f;
; #pragma unroll
;     for (int i = 0; i < 4; ++i) ss += v[i].x * v[i].x + v[i].y * v[i].y + v[i].z * v[i].z + v[i].w * v[i].w;
; #pragma unroll
;     for (int o = 1; o < 64; o <<= 1) ss += __shfl_xor(ss, o);
;     float rstd = rsqrtf(ss * (1.f / DM) + 1e-6f);
; #pragma unroll
;     for (int i = 0; i < 4; ++i) {
;       int c = (i * 64 + lane) * 4;
;       float a0 = v[i].x * rstd * ww[i].x, a1 = v[i].y * rstd * ww[i].y, a2 = v[i].z * rstd * ww[i].z, a3 = v[i].w * rstd * ww[i].w;
;       if (MODE == 0) {
;         uint2 o2; o2.x = pack2(a0, a1); o2.y = pack2(a2, a3);
;         *(uint2*)(dstb + (size_t)row * DM + c) = o2;
;       } else {
;         float4 o4; o4.x = a0; o4.y = a1; o4.z = a2; o4.w = a3;
;         *(float4*)(dstf + (size_t)row * DM + c) = o4;
;       }
;     }
.LBB0_15:
	s_cmp_gt_i32 s52, 20
	s_cbranch_scc0 .LBB0_23
	s_mov_b64 s[18:19], -1
	s_mov_b64 s[8:9], 0
	s_cmp_eq_u32 s52, 21
	s_cbranch_scc0 .LBB0_23
	v_mov_b32_e32 v34, v210
	v_readlane_b32 s0, v253, 5
	v_ashrrev_i32_e32 v0, 6, v34
	s_nop 0
	v_add_u32_e32 v50, s0, v0
	s_movk_i32 s0, 0x4000
	v_cmp_gt_i32_e32 vcc, s0, v50
	s_and_saveexec_b64 s[18:19], vcc
	s_cbranch_execz .LBB0_22
	v_ashrrev_i32_e32 v51, 31, v50
	v_lshlrev_b32_e32 v0, 4, v34
	s_waitcnt vmcnt(17)
	v_lshlrev_b64 v[18:19], 12, v[50:51]
	v_and_b32_e32 v0, 0x3f0, v0
	v_lshl_add_u64 v[52:53], s[22:23], 0, v[18:19]
	v_lshl_add_u64 v[26:27], v[52:53], 0, v[0:1]
	v_readlane_b32 s38, v253, 3
	v_readlane_b32 s39, v253, 4
	s_load_dword s40, s[38:39], 0x0
	s_waitcnt lgkmcnt(0)
	s_cmpk_lg_u32 s40, 0x200
	s_cbranch_scc1 .Lrmsc_std
	global_load_dwordx4 v[2:5], v0, s[20:21]
	global_load_dwordx4 v[6:9], v0, s[20:21] offset:1024
	global_load_dwordx4 v[10:13], v0, s[20:21] offset:2048
	global_load_dwordx4 v[14:17], v0, s[20:21] offset:3072
	v_bfe_u32 v146, v50, 2, 3
	v_lshrrev_b32_e32 v147, 5, v50
	v_and_b32_e32 v148, 3, v50
	v_lshlrev_b32_e32 v146, 11, v146
	v_lshl_or_b32 v147, v147, 2, v148
	v_or_b32_e32 v146, v146, v147
	v_sub_u32_e32 v148, v146, v50
	v_mov_b32_e32 v147, 0
	v_ashrrev_i32_e32 v149, 31, v148
	v_lshlrev_b64 v[148:149], 12, v[148:149]
	v_lshl_add_u64 v[154:155], v[26:27], 0, v[148:149]
	s_mov_b32 s38, 0x100000
	s_mov_b32 s39, 0
	v_mov_b32_e32 v156, v154
	v_mov_b32_e32 v157, v155
	global_load_dwordx4 v[18:21], v[154:155], off
	global_load_dwordx4 v[22:25], v[154:155], off offset:1024
	global_load_dwordx4 v[26:29], v[154:155], off offset:2048
	global_load_dwordx4 v[30:33], v[154:155], off offset:3072
	v_lshl_add_u64 v[154:155], v[154:155], 0, s[38:39]
	global_load_dwordx4 v[34:37], v[154:155], off
	global_load_dwordx4 v[38:41], v[154:155], off offset:1024
	global_load_dwordx4 v[42:45], v[154:155], off offset:2048
	global_load_dwordx4 v[46:49], v[154:155], off offset:3072
	v_lshl_add_u64 v[154:155], v[154:155], 0, s[38:39]
	global_load_dwordx4 v[50:53], v[154:155], off
	global_load_dwordx4 v[54:57], v[154:155], off offset:1024
	global_load_dwordx4 v[58:61], v[154:155], off offset:2048
	global_load_dwordx4 v[62:65], v[154:155], off offset:3072
	v_lshl_add_u64 v[154:155], v[154:155], 0, s[38:39]
	global_load_dwordx4 v[66:69], v[154:155], off
	global_load_dwordx4 v[70:73], v[154:155], off offset:1024
	global_load_dwordx4 v[74:77], v[154:155], off offset:2048
	global_load_dwordx4 v[78:81], v[154:155], off offset:3072
	v_lshl_add_u64 v[154:155], v[154:155], 0, s[38:39]
	global_load_dwordx4 v[82:85], v[154:155], off
	global_load_dwordx4 v[86:89], v[154:155], off offset:1024
	global_load_dwordx4 v[90:93], v[154:155], off offset:2048
	global_load_dwordx4 v[94:97], v[154:155], off offset:3072
	v_lshl_add_u64 v[154:155], v[154:155], 0, s[38:39]
	global_load_dwordx4 v[98:101], v[154:155], off
	global_load_dwordx4 v[102:105], v[154:155], off offset:1024
	global_load_dwordx4 v[106:109], v[154:155], off offset:2048
	global_load_dwordx4 v[110:113], v[154:155], off offset:3072
	v_lshl_add_u64 v[154:155], v[154:155], 0, s[38:39]
	global_load_dwordx4 v[114:117], v[154:155], off
	global_load_dwordx4 v[118:121], v[154:155], off offset:1024
	global_load_dwordx4 v[122:125], v[154:155], off offset:2048
	global_load_dwordx4 v[126:129], v[154:155], off offset:3072
	v_lshl_add_u64 v[154:155], v[154:155], 0, s[38:39]
	global_load_dwordx4 v[130:133], v[154:155], off
	global_load_dwordx4 v[134:137], v[154:155], off offset:1024
	global_load_dwordx4 v[138:141], v[154:155], off offset:2048
	global_load_dwordx4 v[142:145], v[154:155], off offset:3072
	s_waitcnt vmcnt(28)
	v_mul_f32_e32 v146, v22, v22
	v_mul_f32_e32 v147, v18, v18
	v_fmac_f32_e32 v146, v23, v23
	v_fmac_f32_e32 v147, v19, v19
	v_fmac_f32_e32 v146, v24, v24
	v_fmac_f32_e32 v147, v20, v20
	v_fmac_f32_e32 v146, v25, v25
	v_fmac_f32_e32 v147, v21, v21
	v_mul_f32_e32 v148, v30, v30
	v_mul_f32_e32 v149, v26, v26
	v_fmac_f32_e32 v148, v31, v31
	v_fmac_f32_e32 v149, v27, v27
	v_fmac_f32_e32 v148, v32, v32
	v_fmac_f32_e32 v149, v28, v28
	v_fmac_f32_e32 v148, v33, v33
	v_fmac_f32_e32 v149, v29, v29
	v_add_f32_e32 v150, v146, v147
	v_add_f32_e32 v150, v149, v150
	v_add_f32_e32 v150, v148, v150
	s_nop 1
	v_add_f32_dpp v150, v150, v150 quad_perm:[1,0,3,2] row_mask:0xf bank_mask:0xf
	s_nop 1
	v_add_f32_dpp v150, v150, v150 quad_perm:[2,3,0,1] row_mask:0xf bank_mask:0xf
	s_nop 1
	v_add_f32_dpp v150, v150, v150 row_half_mirror row_mask:0xf bank_mask:0xf
	s_nop 1
	v_add_f32_dpp v150, v150, v150 row_mirror row_mask:0xf bank_mask:0xf
	v_mov_b32_e32 v151, v150
	s_nop 1
	v_permlane16_swap_b32_e32 v150, v151
	s_nop 1
	v_add_f32_e32 v150, v150, v151
	v_mov_b32_e32 v151, v150
	s_nop 1
	v_permlane32_swap_b32_e32 v150, v151
	s_nop 1
	v_add_f32_e32 v150, v150, v151
	v_fmamk_f32 v150, v150, 0x3a800000, v211
	v_cmp_gt_f32_e32 vcc, 0x800000, v150
	v_mul_f32_e32 v151, 0x4b800000, v150
	s_nop 0
	v_cndmask_b32_e32 v150, v150, v151, vcc
	v_rsq_f32_e32 v150, v150
	s_nop 0
	v_mul_f32_e32 v151, 0x45800000, v150
	v_cndmask_b32_e32 v150, v150, v151, vcc
	v_mul_f32_e32 v18, v18, v150
	v_mul_f32_e32 v19, v19, v150
	v_mul_f32_e32 v20, v20, v150
	v_mul_f32_e32 v21, v21, v150
	v_mul_f32_e32 v18, v2, v18
	v_mul_f32_e32 v19, v3, v19
	v_mul_f32_e32 v20, v4, v20
	v_mul_f32_e32 v21, v5, v21
	global_store_dwordx4 v[156:157], v[18:21], off
	v_mul_f32_e32 v22, v22, v150
	v_mul_f32_e32 v23, v23, v150
	v_mul_f32_e32 v24, v24, v150
	v_mul_f32_e32 v25, v25, v150
	v_mul_f32_e32 v22, v6, v22
	v_mul_f32_e32 v23, v7, v23
	v_mul_f32_e32 v24, v8, v24
	v_mul_f32_e32 v25, v9, v25
	global_store_dwordx4 v[156:157], v[22:25], off offset:1024
	v_mul_f32_e32 v26, v26, v150
	v_mul_f32_e32 v27, v27, v150
	v_mul_f32_e32 v28, v28, v150
	v_mul_f32_e32 v29, v29, v150
	v_mul_f32_e32 v26, v10, v26
	v_mul_f32_e32 v27, v11, v27
	v_mul_f32_e32 v28, v12, v28
	v_mul_f32_e32 v29, v13, v29
	global_store_dwordx4 v[156:157], v[26:29], off offset:2048
	v_mul_f32_e32 v30, v30, v150
	v_mul_f32_e32 v31, v31, v150
	v_mul_f32_e32 v32, v32, v150
	v_mul_f32_e32 v33, v33, v150
	v_mul_f32_e32 v30, v14, v30
	v_mul_f32_e32 v31, v15, v31
	v_mul_f32_e32 v32, v16, v32
	v_mul_f32_e32 v33, v17, v33
	global_store_dwordx4 v[156:157], v[30:33], off offset:3072
	v_lshl_add_u64 v[156:157], v[156:157], 0, s[38:39]
	s_waitcnt vmcnt(28)
; template <int MODE>
; __device__ void phase_rmsnorm(const float* src, const float* __restrict__ w, u16* __restrict__ dstb, float* dstf) {
;     ...
;     float ss = 0.f;
; #pragma unroll
;     for (int i = 0; i < 4; ++i) ss += v[i].x * v[i].x + v[i].y * v[i].y + v[i].z * v[i].z + v[i].w * v[i].w;
; #pragma unroll
;     for (int o = 1; o < 64; o <<= 1) ss += __shfl_xor(ss, o);
;     float rstd = rsqrtf(ss * (1.f / DM) + 1e-6f);
; #pragma unroll
;     for (int i = 0; i < 4; ++i) {
;       int c = (i * 64 + lane) * 4;
;       float a0 = v[i].x * rstd * ww[i].x, a1 = v[i].y * rstd * ww[i].y, a2 = v[i].z * rstd * ww[i].z, a3 = v[i].w * rstd * ww[i].w;
;       if (MODE == 0) {
;         uint2 o2; o2.x = pack2(a0, a1); o2.y = pack2(a2, a3);
;         *(uint2*)(dstb + (size_t)row * DM + c) = o2;
;       } else {
;         float4 o4; o4.x = a0; o4.y = a1; o4.z = a2; o4.w = a3;
;         *(float4*)(dstf + (size_t)row * DM + c) = o4;
;       }
;     }
	v_mul_f32_e32 v146, v38, v38
	v_mul_f32_e32 v147, v34, v34
	v_fmac_f32_e32 v146, v39, v39
	v_fmac_f32_e32 v147, v35, v35
	v_fmac_f32_e32 v146, v40, v40
	v_fmac_f32_e32 v147, v36, v36
	v_fmac_f32_e32 v146, v41, v41
	v_fmac_f32_e32 v147, v37, v37
	v_mul_f32_e32 v148, v46, v46
	v_mul_f32_e32 v149, v42, v42
	v_fmac_f32_e32 v148, v47, v47
	v_fmac_f32_e32 v149, v43, v43
	v_fmac_f32_e32 v148, v48, v48
	v_fmac_f32_e32 v149, v44, v44
	v_fmac_f32_e32 v148, v49, v49
	v_fmac_f32_e32 v149, v45, v45
	v_add_f32_e32 v150, v146, v147
	v_add_f32_e32 v150, v149, v150
	v_add_f32_e32 v150, v148, v150
	s_nop 1
	v_add_f32_dpp v150, v150, v150 quad_perm:[1,0,3,2] row_mask:0xf bank_mask:0xf
	s_nop 1
	v_add_f32_dpp v150, v150, v150 quad_perm:[2,3,0,1] row_mask:0xf bank_mask:0xf
	s_nop 1
	v_add_f32_dpp v150, v150, v150 row_half_mirror row_mask:0xf bank_mask:0xf
	s_nop 1
	v_add_f32_dpp v150, v150, v150 row_mirror row_mask:0xf bank_mask:0xf
	v_mov_b32_e32 v151, v150
	s_nop 1
	v_permlane16_swap_b32_e32 v150, v151
	s_nop 1
	v_add_f32_e32 v150, v150, v151
	v_mov_b32_e32 v151, v150
	s_nop 1
	v_permlane32_swap_b32_e32 v150, v151
	s_nop 1
	v_add_f32_e32 v150, v150, v151
	v_fmamk_f32 v150, v150, 0x3a800000, v211
	v_cmp_gt_f32_e32 vcc, 0x800000, v150
	v_mul_f32_e32 v151, 0x4b800000, v150
	s_nop 0
	v_cndmask_b32_e32 v150, v150, v151, vcc
	v_rsq_f32_e32 v150, v150
	s_nop 0
	v_mul_f32_e32 v151, 0x45800000, v150
	v_cndmask_b32_e32 v150, v150, v151, vcc
	v_mul_f32_e32 v34, v34, v150
	v_mul_f32_e32 v35, v35, v150
	v_mul_f32_e32 v36, v36, v150
	v_mul_f32_e32 v37, v37, v150
	v_mul_f32_e32 v34, v2, v34
	v_mul_f32_e32 v35, v3, v35
	v_mul_f32_e32 v36, v4, v36
	v_mul_f32_e32 v37, v5, v37
	global_store_dwordx4 v[156:157], v[34:37], off
	v_mul_f32_e32 v38, v38, v150
	v_mul_f32_e32 v39, v39, v150
	v_mul_f32_e32 v40, v40, v150
	v_mul_f32_e32 v41, v41, v150
	v_mul_f32_e32 v38, v6, v38
	v_mul_f32_e32 v39, v7, v39
	v_mul_f32_e32 v40, v8, v40
	v_mul_f32_e32 v41, v9, v41
	global_store_dwordx4 v[156:157], v[38:41], off offset:1024
	v_mul_f32_e32 v42, v42, v150
	v_mul_f32_e32 v43, v43, v150
	v_mul_f32_e32 v44, v44, v150
	v_mul_f32_e32 v45, v45, v150
	v_mul_f32_e32 v42, v10, v42
	v_mul_f32_e32 v43, v11, v43
	v_mul_f32_e32 v44, v12, v44
	v_mul_f32_e32 v45, v13, v45
	global_store_dwordx4 v[156:157], v[42:45], off offset:2048
	v_mul_f32_e32 v46, v46, v150
	v_mul_f32_e32 v47, v47, v150
	v_mul_f32_e32 v48, v48, v150
	v_mul_f32_e32 v49, v49, v150
	v_mul_f32_e32 v46, v14, v46
	v_mul_f32_e32 v47, v15, v47
	v_mul_f32_e32 v48, v16, v48
	v_mul_f32_e32 v49, v17, v49
	global_store_dwordx4 v[156:157], v[46:49], off offset:3072
	v_lshl_add_u64 v[156:157], v[156:157], 0, s[38:39]
	s_waitcnt vmcnt(28)
	v_mul_f32_e32 v146, v54, v54
	v_mul_f32_e32 v147, v50, v50
	v_fmac_f32_e32 v146, v55, v55
	v_fmac_f32_e32 v147, v51, v51
	v_fmac_f32_e32 v146, v56, v56
	v_fmac_f32_e32 v147, v52, v52
	v_fmac_f32_e32 v146, v57, v57
	v_fmac_f32_e32 v147, v53, v53
	v_mul_f32_e32 v148, v62, v62
	v_mul_f32_e32 v149, v58, v58
	v_fmac_f32_e32 v148, v63, v63
	v_fmac_f32_e32 v149, v59, v59
	v_fmac_f32_e32 v148, v64, v64
	v_fmac_f32_e32 v149, v60, v60
	v_fmac_f32_e32 v148, v65, v65
	v_fmac_f32_e32 v149, v61, v61
	v_add_f32_e32 v150, v146, v147
	v_add_f32_e32 v150, v149, v150
	v_add_f32_e32 v150, v148, v150
	s_nop 1
	v_add_f32_dpp v150, v150, v150 quad_perm:[1,0,3,2] row_mask:0xf bank_mask:0xf
	s_nop 1
	v_add_f32_dpp v150, v150, v150 quad_perm:[2,3,0,1] row_mask:0xf bank_mask:0xf
	s_nop 1
	v_add_f32_dpp v150, v150, v150 row_half_mirror row_mask:0xf bank_mask:0xf
	s_nop 1
	v_add_f32_dpp v150, v150, v150 row_mirror row_mask:0xf bank_mask:0xf
	v_mov_b32_e32 v151, v150
	s_nop 1
	v_permlane16_swap_b32_e32 v150, v151
	s_nop 1
	v_add_f32_e32 v150, v150, v151
	v_mov_b32_e32 v151, v150
	s_nop 1
	v_permlane32_swap_b32_e32 v150, v151
	s_nop 1
	v_add_f32_e32 v150, v150, v151
	v_fmamk_f32 v150, v150, 0x3a800000, v211
	v_cmp_gt_f32_e32 vcc, 0x800000, v150
	v_mul_f32_e32 v151, 0x4b800000, v150
	s_nop 0
	v_cndmask_b32_e32 v150, v150, v151, vcc
	v_rsq_f32_e32 v150, v150
	s_nop 0
	v_mul_f32_e32 v151, 0x45800000, v150
	v_cndmask_b32_e32 v150, v150, v151, vcc
	v_mul_f32_e32 v50, v50, v150
	v_mul_f32_e32 v51, v51, v150
	v_mul_f32_e32 v52, v52, v150
	v_mul_f32_e32 v53, v53, v150
	v_mul_f32_e32 v50, v2, v50
	v_mul_f32_e32 v51, v3, v51
	v_mul_f32_e32 v52, v4, v52
	v_mul_f32_e32 v53, v5, v53
	global_store_dwordx4 v[156:157], v[50:53], off
	v_mul_f32_e32 v54, v54, v150
	v_mul_f32_e32 v55, v55, v150
	v_mul_f32_e32 v56, v56, v150
	v_mul_f32_e32 v57, v57, v150
	v_mul_f32_e32 v54, v6, v54
	v_mul_f32_e32 v55, v7, v55
	v_mul_f32_e32 v56, v8, v56
	v_mul_f32_e32 v57, v9, v57
	global_store_dwordx4 v[156:157], v[54:57], off offset:1024
	v_mul_f32_e32 v58, v58, v150
	v_mul_f32_e32 v59, v59, v150
	v_mul_f32_e32 v60, v60, v150
	v_mul_f32_e32 v61, v61, v150
	v_mul_f32_e32 v58, v10, v58
	v_mul_f32_e32 v59, v11, v59
	v_mul_f32_e32 v60, v12, v60
	v_mul_f32_e32 v61, v13, v61
	global_store_dwordx4 v[156:157], v[58:61], off offset:2048
	v_mul_f32_e32 v62, v62, v150
	v_mul_f32_e32 v63, v63, v150
	v_mul_f32_e32 v64, v64, v150
	v_mul_f32_e32 v65, v65, v150
	v_mul_f32_e32 v62, v14, v62
	v_mul_f32_e32 v63, v15, v63
	v_mul_f32_e32 v64, v16, v64
	v_mul_f32_e32 v65, v17, v65
	global_store_dwordx4 v[156:157], v[62:65], off offset:3072
	v_lshl_add_u64 v[156:157], v[156:157], 0, s[38:39]
	s_waitcnt vmcnt(28)
; template <int MODE>
; __device__ void phase_rmsnorm(const float* src, const float* __restrict__ w, u16* __restrict__ dstb, float* dstf) {
;     ...
;     float ss = 0.f;
; #pragma unroll
;     for (int i = 0; i < 4; ++i) ss += v[i].x * v[i].x + v[i].y * v[i].y + v[i].z * v[i].z + v[i].w * v[i].w;
; #pragma unroll
;     for (int o = 1; o < 64; o <<= 1) ss += __shfl_xor(ss, o);
;     float rstd = rsqrtf(ss * (1.f / DM) + 1e-6f);
; #pragma unroll
;     for (int i = 0; i < 4; ++i) {
;       int c = (i * 64 + lane) * 4;
;       float a0 = v[i].x * rstd * ww[i].x, a1 = v[i].y * rstd * ww[i].y, a2 = v[i].z * rstd * ww[i].z, a3 = v[i].w * rstd * ww[i].w;
;       if (MODE == 0) {
;         uint2 o2; o2.x = pack2(a0, a1); o2.y = pack2(a2, a3);
;         *(uint2*)(dstb + (size_t)row * DM + c) = o2;
;       } else {
;         float4 o4; o4.x = a0; o4.y = a1; o4.z = a2; o4.w = a3;
;         *(float4*)(dstf + (size_t)row * DM + c) = o4;
;       }
;     }
	v_mul_f32_e32 v146, v70, v70
	v_mul_f32_e32 v147, v66, v66
	v_fmac_f32_e32 v146, v71, v71
	v_fmac_f32_e32 v147, v67, v67
	v_fmac_f32_e32 v146, v72, v72
	v_fmac_f32_e32 v147, v68, v68
	v_fmac_f32_e32 v146, v73, v73
	v_fmac_f32_e32 v147, v69, v69
	v_mul_f32_e32 v148, v78, v78
	v_mul_f32_e32 v149, v74, v74
	v_fmac_f32_e32 v148, v79, v79
	v_fmac_f32_e32 v149, v75, v75
	v_fmac_f32_e32 v148, v80, v80
	v_fmac_f32_e32 v149, v76, v76
	v_fmac_f32_e32 v148, v81, v81
	v_fmac_f32_e32 v149, v77, v77
	v_add_f32_e32 v150, v146, v147
	v_add_f32_e32 v150, v149, v150
	v_add_f32_e32 v150, v148, v150
	s_nop 1
	v_add_f32_dpp v150, v150, v150 quad_perm:[1,0,3,2] row_mask:0xf bank_mask:0xf
	s_nop 1
	v_add_f32_dpp v150, v150, v150 quad_perm:[2,3,0,1] row_mask:0xf bank_mask:0xf
	s_nop 1
	v_add_f32_dpp v150, v150, v150 row_half_mirror row_mask:0xf bank_mask:0xf
	s_nop 1
	v_add_f32_dpp v150, v150, v150 row_mirror row_mask:0xf bank_mask:0xf
	v_mov_b32_e32 v151, v150
	s_nop 1
	v_permlane16_swap_b32_e32 v150, v151
	s_nop 1
	v_add_f32_e32 v150, v150, v151
	v_mov_b32_e32 v151, v150
	s_nop 1
	v_permlane32_swap_b32_e32 v150, v151
	s_nop 1
	v_add_f32_e32 v150, v150, v151
	v_fmamk_f32 v150, v150, 0x3a800000, v211
	v_cmp_gt_f32_e32 vcc, 0x800000, v150
	v_mul_f32_e32 v151, 0x4b800000, v150
	s_nop 0
	v_cndmask_b32_e32 v150, v150, v151, vcc
	v_rsq_f32_e32 v150, v150
	s_nop 0
	v_mul_f32_e32 v151, 0x45800000, v150
	v_cndmask_b32_e32 v150, v150, v151, vcc
	v_mul_f32_e32 v66, v66, v150
	v_mul_f32_e32 v67, v67, v150
	v_mul_f32_e32 v68, v68, v150
	v_mul_f32_e32 v69, v69, v150
	v_mul_f32_e32 v66, v2, v66
	v_mul_f32_e32 v67, v3, v67
	v_mul_f32_e32 v68, v4, v68
	v_mul_f32_e32 v69, v5, v69
	global_store_dwordx4 v[156:157], v[66:69], off
	v_mul_f32_e32 v70, v70, v150
	v_mul_f32_e32 v71, v71, v150
	v_mul_f32_e32 v72, v72, v150
	v_mul_f32_e32 v73, v73, v150
	v_mul_f32_e32 v70, v6, v70
	v_mul_f32_e32 v71, v7, v71
	v_mul_f32_e32 v72, v8, v72
	v_mul_f32_e32 v73, v9, v73
	global_store_dwordx4 v[156:157], v[70:73], off offset:1024
	v_mul_f32_e32 v74, v74, v150
	v_mul_f32_e32 v75, v75, v150
	v_mul_f32_e32 v76, v76, v150
	v_mul_f32_e32 v77, v77, v150
	v_mul_f32_e32 v74, v10, v74
	v_mul_f32_e32 v75, v11, v75
	v_mul_f32_e32 v76, v12, v76
	v_mul_f32_e32 v77, v13, v77
	global_store_dwordx4 v[156:157], v[74:77], off offset:2048
	v_mul_f32_e32 v78, v78, v150
	v_mul_f32_e32 v79, v79, v150
	v_mul_f32_e32 v80, v80, v150
	v_mul_f32_e32 v81, v81, v150
	v_mul_f32_e32 v78, v14, v78
	v_mul_f32_e32 v79, v15, v79
	v_mul_f32_e32 v80, v16, v80
	v_mul_f32_e32 v81, v17, v81
	global_store_dwordx4 v[156:157], v[78:81], off offset:3072
	v_lshl_add_u64 v[156:157], v[156:157], 0, s[38:39]
	s_waitcnt vmcnt(28)
	v_mul_f32_e32 v146, v86, v86
	v_mul_f32_e32 v147, v82, v82
	v_fmac_f32_e32 v146, v87, v87
	v_fmac_f32_e32 v147, v83, v83
	v_fmac_f32_e32 v146, v88, v88
	v_fmac_f32_e32 v147, v84, v84
	v_fmac_f32_e32 v146, v89, v89
	v_fmac_f32_e32 v147, v85, v85
	v_mul_f32_e32 v148, v94, v94
	v_mul_f32_e32 v149, v90, v90
	v_fmac_f32_e32 v148, v95, v95
	v_fmac_f32_e32 v149, v91, v91
	v_fmac_f32_e32 v148, v96, v96
	v_fmac_f32_e32 v149, v92, v92
	v_fmac_f32_e32 v148, v97, v97
	v_fmac_f32_e32 v149, v93, v93
	v_add_f32_e32 v150, v146, v147
	v_add_f32_e32 v150, v149, v150
	v_add_f32_e32 v150, v148, v150
	s_nop 1
	v_add_f32_dpp v150, v150, v150 quad_perm:[1,0,3,2] row_mask:0xf bank_mask:0xf
	s_nop 1
	v_add_f32_dpp v150, v150, v150 quad_perm:[2,3,0,1] row_mask:0xf bank_mask:0xf
	s_nop 1
	v_add_f32_dpp v150, v150, v150 row_half_mirror row_mask:0xf bank_mask:0xf
	s_nop 1
	v_add_f32_dpp v150, v150, v150 row_mirror row_mask:0xf bank_mask:0xf
	v_mov_b32_e32 v151, v150
	s_nop 1
	v_permlane16_swap_b32_e32 v150, v151
	s_nop 1
	v_add_f32_e32 v150, v150, v151
	v_mov_b32_e32 v151, v150
	s_nop 1
	v_permlane32_swap_b32_e32 v150, v151
	s_nop 1
	v_add_f32_e32 v150, v150, v151
	v_fmamk_f32 v150, v150, 0x3a800000, v211
	v_cmp_gt_f32_e32 vcc, 0x800000, v150
	v_mul_f32_e32 v151, 0x4b800000, v150
	s_nop 0
	v_cndmask_b32_e32 v150, v150, v151, vcc
	v_rsq_f32_e32 v150, v150
	s_nop 0
	v_mul_f32_e32 v151, 0x45800000, v150
	v_cndmask_b32_e32 v150, v150, v151, vcc
	v_mul_f32_e32 v82, v82, v150
	v_mul_f32_e32 v83, v83, v150
	v_mul_f32_e32 v84, v84, v150
	v_mul_f32_e32 v85, v85, v150
	v_mul_f32_e32 v82, v2, v82
	v_mul_f32_e32 v83, v3, v83
	v_mul_f32_e32 v84, v4, v84
	v_mul_f32_e32 v85, v5, v85
	global_store_dwordx4 v[156:157], v[82:85], off
	v_mul_f32_e32 v86, v86, v150
	v_mul_f32_e32 v87, v87, v150
	v_mul_f32_e32 v88, v88, v150
	v_mul_f32_e32 v89, v89, v150
	v_mul_f32_e32 v86, v6, v86
	v_mul_f32_e32 v87, v7, v87
	v_mul_f32_e32 v88, v8, v88
	v_mul_f32_e32 v89, v9, v89
	global_store_dwordx4 v[156:157], v[86:89], off offset:1024
	v_mul_f32_e32 v90, v90, v150
	v_mul_f32_e32 v91, v91, v150
	v_mul_f32_e32 v92, v92, v150
	v_mul_f32_e32 v93, v93, v150
	v_mul_f32_e32 v90, v10, v90
	v_mul_f32_e32 v91, v11, v91
	v_mul_f32_e32 v92, v12, v92
	v_mul_f32_e32 v93, v13, v93
	global_store_dwordx4 v[156:157], v[90:93], off offset:2048
	v_mul_f32_e32 v94, v94, v150
	v_mul_f32_e32 v95, v95, v150
	v_mul_f32_e32 v96, v96, v150
	v_mul_f32_e32 v97, v97, v150
	v_mul_f32_e32 v94, v14, v94
	v_mul_f32_e32 v95, v15, v95
	v_mul_f32_e32 v96, v16, v96
	v_mul_f32_e32 v97, v17, v97
	global_store_dwordx4 v[156:157], v[94:97], off offset:3072
	v_lshl_add_u64 v[156:157], v[156:157], 0, s[38:39]
	s_waitcnt vmcnt(28)
; template <int MODE>
; __device__ void phase_rmsnorm(const float* src, const float* __restrict__ w, u16* __restrict__ dstb, float* dstf) {
;     ...
;     float ss = 0.f;
; #pragma unroll
;     for (int i = 0; i < 4; ++i) ss += v[i].x * v[i].x + v[i].y * v[i].y + v[i].z * v[i].z + v[i].w * v[i].w;
; #pragma unroll
;     for (int o = 1; o < 64; o <<= 1) ss += __shfl_xor(ss, o);
;     float rstd = rsqrtf(ss * (1.f / DM) + 1e-6f);
; #pragma unroll
;     for (int i = 0; i < 4; ++i) {
;       int c = (i * 64 + lane) * 4;
;       float a0 = v[i].x * rstd * ww[i].x, a1 = v[i].y * rstd * ww[i].y, a2 = v[i].z * rstd * ww[i].z, a3 = v[i].w * rstd * ww[i].w;
;       if (MODE == 0) {
;         uint2 o2; o2.x = pack2(a0, a1); o2.y = pack2(a2, a3);
;         *(uint2*)(dstb + (size_t)row * DM + c) = o2;
;       } else {
;         float4 o4; o4.x = a0; o4.y = a1; o4.z = a2; o4.w = a3;
;         *(float4*)(dstf + (size_t)row * DM + c) = o4;
;       }
;     }
	v_mul_f32_e32 v146, v102, v102
	v_mul_f32_e32 v147, v98, v98
	v_fmac_f32_e32 v146, v103, v103
	v_fmac_f32_e32 v147, v99, v99
	v_fmac_f32_e32 v146, v104, v104
	v_fmac_f32_e32 v147, v100, v100
	v_fmac_f32_e32 v146, v105, v105
	v_fmac_f32_e32 v147, v101, v101
	v_mul_f32_e32 v148, v110, v110
	v_mul_f32_e32 v149, v106, v106
	v_fmac_f32_e32 v148, v111, v111
	v_fmac_f32_e32 v149, v107, v107
	v_fmac_f32_e32 v148, v112, v112
	v_fmac_f32_e32 v149, v108, v108
	v_fmac_f32_e32 v148, v113, v113
	v_fmac_f32_e32 v149, v109, v109
	v_add_f32_e32 v150, v146, v147
	v_add_f32_e32 v150, v149, v150
	v_add_f32_e32 v150, v148, v150
	s_nop 1
	v_add_f32_dpp v150, v150, v150 quad_perm:[1,0,3,2] row_mask:0xf bank_mask:0xf
	s_nop 1
	v_add_f32_dpp v150, v150, v150 quad_perm:[2,3,0,1] row_mask:0xf bank_mask:0xf
	s_nop 1
	v_add_f32_dpp v150, v150, v150 row_half_mirror row_mask:0xf bank_mask:0xf
	s_nop 1
	v_add_f32_dpp v150, v150, v150 row_mirror row_mask:0xf bank_mask:0xf
	v_mov_b32_e32 v151, v150
	s_nop 1
	v_permlane16_swap_b32_e32 v150, v151
	s_nop 1
	v_add_f32_e32 v150, v150, v151
	v_mov_b32_e32 v151, v150
	s_nop 1
	v_permlane32_swap_b32_e32 v150, v151
	s_nop 1
	v_add_f32_e32 v150, v150, v151
	v_fmamk_f32 v150, v150, 0x3a800000, v211
	v_cmp_gt_f32_e32 vcc, 0x800000, v150
	v_mul_f32_e32 v151, 0x4b800000, v150
	s_nop 0
	v_cndmask_b32_e32 v150, v150, v151, vcc
	v_rsq_f32_e32 v150, v150
	s_nop 0
	v_mul_f32_e32 v151, 0x45800000, v150
	v_cndmask_b32_e32 v150, v150, v151, vcc
	v_mul_f32_e32 v98, v98, v150
	v_mul_f32_e32 v99, v99, v150
	v_mul_f32_e32 v100, v100, v150
	v_mul_f32_e32 v101, v101, v150
	v_mul_f32_e32 v98, v2, v98
	v_mul_f32_e32 v99, v3, v99
	v_mul_f32_e32 v100, v4, v100
	v_mul_f32_e32 v101, v5, v101
	global_store_dwordx4 v[156:157], v[98:101], off
	v_mul_f32_e32 v102, v102, v150
	v_mul_f32_e32 v103, v103, v150
	v_mul_f32_e32 v104, v104, v150
	v_mul_f32_e32 v105, v105, v150
	v_mul_f32_e32 v102, v6, v102
	v_mul_f32_e32 v103, v7, v103
	v_mul_f32_e32 v104, v8, v104
	v_mul_f32_e32 v105, v9, v105
	global_store_dwordx4 v[156:157], v[102:105], off offset:1024
	v_mul_f32_e32 v106, v106, v150
	v_mul_f32_e32 v107, v107, v150
	v_mul_f32_e32 v108, v108, v150
	v_mul_f32_e32 v109, v109, v150
	v_mul_f32_e32 v106, v10, v106
	v_mul_f32_e32 v107, v11, v107
	v_mul_f32_e32 v108, v12, v108
	v_mul_f32_e32 v109, v13, v109
	global_store_dwordx4 v[156:157], v[106:109], off offset:2048
	v_mul_f32_e32 v110, v110, v150
	v_mul_f32_e32 v111, v111, v150
	v_mul_f32_e32 v112, v112, v150
	v_mul_f32_e32 v113, v113, v150
	v_mul_f32_e32 v110, v14, v110
	v_mul_f32_e32 v111, v15, v111
	v_mul_f32_e32 v112, v16, v112
	v_mul_f32_e32 v113, v17, v113
	global_store_dwordx4 v[156:157], v[110:113], off offset:3072
	v_lshl_add_u64 v[156:157], v[156:157], 0, s[38:39]
	s_waitcnt vmcnt(28)
	v_mul_f32_e32 v146, v118, v118
	v_mul_f32_e32 v147, v114, v114
	v_fmac_f32_e32 v146, v119, v119
	v_fmac_f32_e32 v147, v115, v115
	v_fmac_f32_e32 v146, v120, v120
	v_fmac_f32_e32 v147, v116, v116
	v_fmac_f32_e32 v146, v121, v121
	v_fmac_f32_e32 v147, v117, v117
	v_mul_f32_e32 v148, v126, v126
	v_mul_f32_e32 v149, v122, v122
	v_fmac_f32_e32 v148, v127, v127
	v_fmac_f32_e32 v149, v123, v123
	v_fmac_f32_e32 v148, v128, v128
	v_fmac_f32_e32 v149, v124, v124
	v_fmac_f32_e32 v148, v129, v129
	v_fmac_f32_e32 v149, v125, v125
	v_add_f32_e32 v150, v146, v147
	v_add_f32_e32 v150, v149, v150
	v_add_f32_e32 v150, v148, v150
	s_nop 1
	v_add_f32_dpp v150, v150, v150 quad_perm:[1,0,3,2] row_mask:0xf bank_mask:0xf
	s_nop 1
	v_add_f32_dpp v150, v150, v150 quad_perm:[2,3,0,1] row_mask:0xf bank_mask:0xf
	s_nop 1
	v_add_f32_dpp v150, v150, v150 row_half_mirror row_mask:0xf bank_mask:0xf
	s_nop 1
	v_add_f32_dpp v150, v150, v150 row_mirror row_mask:0xf bank_mask:0xf
	v_mov_b32_e32 v151, v150
	s_nop 1
	v_permlane16_swap_b32_e32 v150, v151
	s_nop 1
	v_add_f32_e32 v150, v150, v151
	v_mov_b32_e32 v151, v150
	s_nop 1
	v_permlane32_swap_b32_e32 v150, v151
	s_nop 1
	v_add_f32_e32 v150, v150, v151
	v_fmamk_f32 v150, v150, 0x3a800000, v211
	v_cmp_gt_f32_e32 vcc, 0x800000, v150
	v_mul_f32_e32 v151, 0x4b800000, v150
	s_nop 0
	v_cndmask_b32_e32 v150, v150, v151, vcc
	v_rsq_f32_e32 v150, v150
	s_nop 0
	v_mul_f32_e32 v151, 0x45800000, v150
	v_cndmask_b32_e32 v150, v150, v151, vcc
	v_mul_f32_e32 v114, v114, v150
	v_mul_f32_e32 v115, v115, v150
	v_mul_f32_e32 v116, v116, v150
	v_mul_f32_e32 v117, v117, v150
	v_mul_f32_e32 v114, v2, v114
	v_mul_f32_e32 v115, v3, v115
	v_mul_f32_e32 v116, v4, v116
	v_mul_f32_e32 v117, v5, v117
	global_store_dwordx4 v[156:157], v[114:117], off
	v_mul_f32_e32 v118, v118, v150
	v_mul_f32_e32 v119, v119, v150
	v_mul_f32_e32 v120, v120, v150
	v_mul_f32_e32 v121, v121, v150
	v_mul_f32_e32 v118, v6, v118
	v_mul_f32_e32 v119, v7, v119
	v_mul_f32_e32 v120, v8, v120
	v_mul_f32_e32 v121, v9, v121
	global_store_dwordx4 v[156:157], v[118:121], off offset:1024
	v_mul_f32_e32 v122, v122, v150
	v_mul_f32_e32 v123, v123, v150
	v_mul_f32_e32 v124, v124, v150
	v_mul_f32_e32 v125, v125, v150
	v_mul_f32_e32 v122, v10, v122
	v_mul_f32_e32 v123, v11, v123
	v_mul_f32_e32 v124, v12, v124
	v_mul_f32_e32 v125, v13, v125
	global_store_dwordx4 v[156:157], v[122:125], off offset:2048
	v_mul_f32_e32 v126, v126, v150
	v_mul_f32_e32 v127, v127, v150
	v_mul_f32_e32 v128, v128, v150
	v_mul_f32_e32 v129, v129, v150
	v_mul_f32_e32 v126, v14, v126
	v_mul_f32_e32 v127, v15, v127
	v_mul_f32_e32 v128, v16, v128
	v_mul_f32_e32 v129, v17, v129
	global_store_dwordx4 v[156:157], v[126:129], off offset:3072
	v_lshl_add_u64 v[156:157], v[156:157], 0, s[38:39]
	s_waitcnt vmcnt(28)
; __device__ __forceinline__ int otid() { int t = threadIdx.x; asm volatile("" : "+v"(t)); return t; }
; template <int MODE>
; __device__ void phase_rmsnorm(const float* src, const float* __restrict__ w, u16* __restrict__ dstb, float* dstf) {
;   const int tid_ = otid();
;   const int lane = tid_ & 63;
;   const int gw = blockIdx.x * 4 + (tid_ >> 6);
;   const int nw = gridDim.x * 4;
;   float4 ww[4];
; #pragma unroll
;   for (int i = 0; i < 4; ++i) ww[i] = *(const float4*)(w + (i * 64 + lane) * 4);
;   float4 v[4], nv[4];
;   int row = gw;
;   if (row < TOK) {
; #pragma unroll
;     for (int i = 0; i < 4; ++i) v[i] = *(const float4*)(src + (size_t)row * DM + (i * 64 + lane) * 4);
;   }
;   while (row < TOK) {
;     const int nrow = row + nw;
;     if (nrow < TOK) {
; #pragma unroll
;       for (int i = 0; i < 4; ++i) nv[i] = *(const float4*)(src + (size_t)nrow * DM + (i * 64 + lane) * 4);
;     }
;     float ss = 0.f;
; #pragma unroll
;     for (int i = 0; i < 4; ++i) ss += v[i].x * v[i].x + v[i].y * v[i].y + v[i].z * v[i].z + v[i].w * v[i].w;
; #pragma unroll
;     for (int o = 1; o < 64; o <<= 1) ss += __shfl_xor(ss, o);
;     float rstd = rsqrtf(ss * (1.f / DM) + 1e-6f);
; #pragma unroll
;     for (int i = 0; i < 4; ++i) {
;       int c = (i * 64 + lane) * 4;
;       float a0 = v[i].x * rstd * ww[i].x, a1 = v[i].y * rstd * ww[i].y, a2 = v[i].z * rstd * ww[i].z, a3 = v[i].w * rstd * ww[i].w;
;       if (MODE == 0) {
;         uint2 o2; o2.x = pack2(a0, a1); o2.y = pack2(a2, a3);
;         *(uint2*)(dstb + (size_t)row * DM + c) = o2;
;       } else {
;         float4 o4; o4.x = a0; o4.y = a1; o4.z = a2; o4.w = a3;
;         *(float4*)(dstf + (size_t)row * DM + c) = o4;
;       }
;     }
	v_mul_f32_e32 v146, v134, v134
	v_mul_f32_e32 v147, v130, v130
	v_fmac_f32_e32 v146, v135, v135
	v_fmac_f32_e32 v147, v131, v131
	v_fmac_f32_e32 v146, v136, v136
	v_fmac_f32_e32 v147, v132, v132
	v_fmac_f32_e32 v146, v137, v137
	v_fmac_f32_e32 v147, v133, v133
	v_mul_f32_e32 v148, v142, v142
	v_mul_f32_e32 v149, v138, v138
	v_fmac_f32_e32 v148, v143, v143
	v_fmac_f32_e32 v149, v139, v139
	v_fmac_f32_e32 v148, v144, v144
	v_fmac_f32_e32 v149, v140, v140
	v_fmac_f32_e32 v148, v145, v145
	v_fmac_f32_e32 v149, v141, v141
	v_add_f32_e32 v150, v146, v147
	v_add_f32_e32 v150, v149, v150
	v_add_f32_e32 v150, v148, v150
	s_nop 1
	v_add_f32_dpp v150, v150, v150 quad_perm:[1,0,3,2] row_mask:0xf bank_mask:0xf
	s_nop 1
	v_add_f32_dpp v150, v150, v150 quad_perm:[2,3,0,1] row_mask:0xf bank_mask:0xf
	s_nop 1
	v_add_f32_dpp v150, v150, v150 row_half_mirror row_mask:0xf bank_mask:0xf
	s_nop 1
	v_add_f32_dpp v150, v150, v150 row_mirror row_mask:0xf bank_mask:0xf
	v_mov_b32_e32 v151, v150
	s_nop 1
	v_permlane16_swap_b32_e32 v150, v151
	s_nop 1
	v_add_f32_e32 v150, v150, v151
	v_mov_b32_e32 v151, v150
	s_nop 1
	v_permlane32_swap_b32_e32 v150, v151
	s_nop 1
	v_add_f32_e32 v150, v150, v151
	v_fmamk_f32 v150, v150, 0x3a800000, v211
	v_cmp_gt_f32_e32 vcc, 0x800000, v150
	v_mul_f32_e32 v151, 0x4b800000, v150
	s_nop 0
	v_cndmask_b32_e32 v150, v150, v151, vcc
	v_rsq_f32_e32 v150, v150
	s_nop 0
	v_mul_f32_e32 v151, 0x45800000, v150
	v_cndmask_b32_e32 v150, v150, v151, vcc
	v_mul_f32_e32 v130, v130, v150
	v_mul_f32_e32 v131, v131, v150
	v_mul_f32_e32 v132, v132, v150
	v_mul_f32_e32 v133, v133, v150
	v_mul_f32_e32 v130, v2, v130
	v_mul_f32_e32 v131, v3, v131
	v_mul_f32_e32 v132, v4, v132
	v_mul_f32_e32 v133, v5, v133
	global_store_dwordx4 v[156:157], v[130:133], off
	v_mul_f32_e32 v134, v134, v150
	v_mul_f32_e32 v135, v135, v150
	v_mul_f32_e32 v136, v136, v150
	v_mul_f32_e32 v137, v137, v150
	v_mul_f32_e32 v134, v6, v134
	v_mul_f32_e32 v135, v7, v135
	v_mul_f32_e32 v136, v8, v136
	v_mul_f32_e32 v137, v9, v137
	global_store_dwordx4 v[156:157], v[134:137], off offset:1024
	v_mul_f32_e32 v138, v138, v150
	v_mul_f32_e32 v139, v139, v150
	v_mul_f32_e32 v140, v140, v150
	v_mul_f32_e32 v141, v141, v150
	v_mul_f32_e32 v138, v10, v138
	v_mul_f32_e32 v139, v11, v139
	v_mul_f32_e32 v140, v12, v140
	v_mul_f32_e32 v141, v13, v141
	global_store_dwordx4 v[156:157], v[138:141], off offset:2048
	v_mul_f32_e32 v142, v142, v150
	v_mul_f32_e32 v143, v143, v150
	v_mul_f32_e32 v144, v144, v150
	v_mul_f32_e32 v145, v145, v150
	v_mul_f32_e32 v142, v14, v142
	v_mul_f32_e32 v143, v15, v143
	v_mul_f32_e32 v144, v16, v144
	v_mul_f32_e32 v145, v17, v145
	global_store_dwordx4 v[156:157], v[142:145], off offset:3072
	s_branch .LBB0_22
.Lrmsc_std:
	global_load_dwordx4 v[2:5], v0, s[20:21]
	global_load_dwordx4 v[6:9], v0, s[20:21] offset:1024
	global_load_dwordx4 v[10:13], v0, s[20:21] offset:2048
	global_load_dwordx4 v[14:17], v0, s[20:21] offset:3072
	global_load_dwordx4 v[30:33], v[26:27], off
	global_load_dwordx4 v[18:21], v[26:27], off offset:1024
	global_load_dwordx4 v[22:25], v[26:27], off offset:2048
	s_nop 0
	global_load_dwordx4 v[26:29], v[26:27], off offset:3072
	v_cmp_lt_i32_e32 vcc, v250, v217
	v_readlane_b32 s0, v253, 3
	v_readlane_b32 s1, v253, 4
	v_cndmask_b32_e32 v0, v215, v250, vcc
	v_cmp_lt_i32_e32 vcc, v251, v217
	v_lshlrev_b32_e32 v51, 2, v0
	s_load_dword s0, s[0:1], 0x0
	v_cndmask_b32_e32 v0, v215, v251, vcc
	v_cmp_lt_i32_e32 vcc, v252, v217
	v_lshlrev_b32_e32 v56, 2, v0
	s_mov_b64 s[38:39], 0
	v_cndmask_b32_e32 v0, v215, v252, vcc
	v_lshlrev_b32_e32 v57, 2, v0
	v_xor_b32_e32 v0, 8, v215
	v_cmp_lt_i32_e32 vcc, v0, v217
	s_waitcnt lgkmcnt(0)
	s_lshl_b32 s24, s0, 2
	s_ashr_i32 s25, s24, 31
	v_cndmask_b32_e32 v0, v215, v0, vcc
	v_cmp_lt_i32_e32 vcc, v214, v217
	v_lshlrev_b32_e32 v58, 2, v0
	s_lshl_b64 s[30:31], s[24:25], 12
	v_cndmask_b32_e32 v0, v215, v214, vcc
	v_cmp_lt_i32_e32 vcc, v229, v217
	v_lshlrev_b32_e32 v59, 2, v0
	s_nop 0
	v_cndmask_b32_e32 v0, v215, v229, vcc
	v_lshlrev_b32_e32 v60, 2, v0
	v_and_b32_e32 v0, 63, v34
	v_add_u32_e32 v34, s24, v50
	v_ashrrev_i32_e32 v35, 31, v34
	v_lshlrev_b64 v[34:35], 12, v[34:35]
	v_lshlrev_b32_e32 v0, 4, v0
	v_lshl_add_u64 v[54:55], s[22:23], 0, v[34:35]
	s_branch .LBB0_20

; __device__ void phase_y(const Params& p, int layer, unsigned char* smem) {
;     ...
;   for (int i = blockIdx.x; i < NI / 2; i += G) {
; #pragma unroll 1
;     for (int h = 0; h < 2; ++h) {
;       int it = h ? (NI - 1 - i) : i;
;       int qt = 63 - (it >> 4); int r = it & 15; int b = r >> 1, g = r & 1;
;       item_nsa(p, layer, b, g, qt, smem);
.LBB0_33:
	s_and_b32 s0, s9, 7
	s_lshl_b32 s0, s0, 1
	s_bfe_u32 s1, s9, 0x10003
	s_or_b32 s0, s0, s1
	s_andn2_b32 s1, s9, 15
	s_or_b32 s0, s0, s1
	v_writelane_b32 v255, s0, 25
	s_xor_b32 s0, s0, 0x3f0
	v_writelane_b32 v255, s0, 24
	s_mov_b64 s[0:1], -1
	s_branch .LBB0_35

; __device__ __forceinline__ int otid() { int t = threadIdx.x; asm volatile("" : "+v"(t)); return t; }
; __device__ __forceinline__ float bf2f(u16 b) { return __uint_as_float(((unsigned)b) << 16); }
; __device__ __forceinline__ float sigmoid_f(float x) { return __builtin_amdgcn_rcpf(1.f + __expf(-x)); }
; __device__ void item_nsa(const Params& p, int layer, int b, int g, int qt, unsigned char* smem) {
;   u16* sK = (u16*)smem;
;   u16* sVt = sK + 64 * 72;
;   u16* sK2 = (u16*)smem;
;   u16* sV2 = sK2 + 128 * 72;
;   float* sImp = (float*)(smem + SM_IMP_OFF);
;   unsigned* sSel = (unsigned*)(smem + SM_MAIN);
;   const int tid = otid(), lane = tid & 63, l15 = lane & 15, quad = lane >> 4;
;   const int wave = __builtin_amdgcn_readfirstlane(tid >> 6);
;   const int q0 = qt * 32;
;   const int hh = g * 4 + wave;
;   int tq[2];
;   tq[0] = q0 + l15; tq[1] = tq[0] + 16;
;   const float slope = exp2f(-(float)(hh + 1));
;   float slope2[2] = {slope * LOG2E, slope * LOG2E};
;   const float c1 = 0.125f * LOG2E;
;   const u16* hb = P_H + (size_t)b * SEQ * HS;
;   bf16x8 qf[2][2];
;   float gate[2][3];
; #pragma unroll
;   for (int n = 0; n < 2; ++n) {
; #pragma unroll
;     for (int ks = 0; ks < 2; ++ks)
;       qf[n][ks] = *(const bf16x8*)(hb + (size_t)tq[n] * HS + C_QC + hh * 64 + ks * 32 + quad * 8);
; #pragma unroll
;     for (int i = 0; i < 3; ++i) gate[n][i] = sigmoid_f(bf2f(hb[(size_t)tq[n] * HS + C_GL + hh * 3 + i]));
;   }
;   f32x4 Of[2][4];
;   {
;     const u16* kc = P_KCMP + (size_t)(b * 2 + g) * 128 * 64;
;     const u16* vc = P_VCMP_T + (size_t)(b * 2 + g) * 64 * 128;
;     __syncthreads();
; #pragma unroll
;     for (int c = tid; c < 1024; c += 256) {
;       int key = c >> 3, kc8 = (c & 7) * 8;
;       *(uint4*)(sK2 + key * 64 + (((c & 7) ^ ((key >> 1) & 7)) * 8)) = *(const uint4*)(kc + key * 64 + kc8);
; __device__ void phase_y(const Params& p, int layer, unsigned char* smem) {
;     ...
;       int it = h ? (NI - 1 - i) : i;
;       int qt = 63 - (it >> 4); int r = it & 15; int b = r >> 1, g = r & 1;
;       item_nsa(p, layer, b, g, qt, smem);
.LBB0_35:
	s_and_b64 s[6:7], s[0:1], exec
	v_readlane_b32 s6, v255, 24
	v_readlane_b32 s7, v255, 25
	s_cselect_b32 s6, s7, s6
	v_mov_b32_e32 v189, v210
	s_ashr_i32 s29, s6, 4
	s_bfe_u32 s35, s6, 0x30001
	s_and_b32 s86, s6, 1
	s_lshl_b32 s25, s86, 2
	v_readfirstlane_b32 s6, v189
	s_ashr_i32 s24, s6, 6
	s_add_i32 s30, s24, s25
	s_add_i32 s6, s30, 1
	v_cvt_f32_i32_e32 v2, s6
	s_sub_i32 s12, 63, s29
	s_mov_b32 s6, 0x42fc0000
	s_lshl_b32 s8, s12, 5
	v_cmp_lt_f32_e64 s[38:39], s6, v2
	s_and_b64 s[6:7], s[38:39], exec
	s_mul_i32 s6, s35, 0xe80000
	v_readlane_b32 s7, v254, 4
	s_cselect_b32 s42, 0xffffffc0, 0
	s_add_u32 s18, s7, s6
	v_and_b32_e32 v120, 15, v189
	s_addc_u32 s19, s33, 0
	s_lshl_b32 s6, s30, 6
	s_mul_i32 s30, s30, 3
	v_or_b32_e32 v200, s8, v120
	s_ashr_i32 s7, s6, 31
	s_ashr_i32 s31, s30, 31
	v_mov_b64_e32 v[12:13], s[18:19]
	v_mad_i64_i32 v[14:15], s[40:41], v200, s3, v[12:13]
	s_lshl_b64 s[6:7], s[6:7], 1
	s_lshl_b64 s[30:31], s[30:31], 1
	v_or_b32_e32 v201, 16, v200
	v_lshl_add_u64 v[4:5], v[14:15], 0, s[6:7]
	v_lshl_add_u64 v[14:15], v[14:15], 0, s[30:31]
	s_mov_b64 s[44:45], 0x1800
	s_movk_i32 s40, 0x1000
	v_bfe_u32 v53, v189, 4, 2
	v_lshl_add_u64 v[16:17], v[14:15], 0, s[44:45]
	v_add_co_u32_e32 v14, vcc, s40, v14
	s_waitcnt vmcnt(17)
	v_mad_i64_i32 v[20:21], s[40:41], v201, s3, v[12:13]
	v_lshlrev_b32_e32 v0, 4, v53
	v_addc_co_u32_e32 v15, vcc, 0, v15, vcc
	v_lshl_add_u64 v[12:13], v[20:21], 0, s[6:7]
	v_lshl_add_u64 v[20:21], v[20:21], 0, s[30:31]
	v_lshl_add_u64 v[8:9], v[4:5], 0, v[0:1]
	s_waitcnt vmcnt(16)
	v_lshl_add_u64 v[22:23], v[20:21], 0, s[44:45]
	v_add_co_u32_e32 v20, vcc, 0x1000, v20
	global_load_dwordx4 v[4:7], v[8:9], off offset:3584
	s_nop 0
	global_load_dwordx4 v[8:11], v[8:9], off offset:3648
	s_nop 0
	global_load_dword v191, v[14:15], off offset:2048
	global_load_ushort v3, v[16:17], off offset:4
	v_lshl_add_u64 v[16:17], v[12:13], 0, v[0:1]
	v_addc_co_u32_e32 v21, vcc, 0, v21, vcc
	global_load_dwordx4 v[12:15], v[16:17], off offset:3584
	s_nop 0
	global_load_dwordx4 v[16:19], v[16:17], off offset:3648
	s_nop 0
	global_load_dword v202, v[20:21], off offset:2048
	s_nop 0
	global_load_ushort v20, v[22:23], off offset:4
	s_movk_i32 s6, 0x400
	v_cmp_gt_i32_e32 vcc, s6, v189
	v_lshlrev_b32_e32 v193, 3, v189
	s_barrier
	s_and_saveexec_b64 s[6:7], vcc
	s_cbranch_execz .LBB0_40
	s_lshl_b32 s30, s35, 15
	s_lshl_b32 s31, s86, 14
	s_or_b32 s43, s30, s31
	v_readlane_b32 s30, v254, 5
	v_readlane_b32 s31, v254, 6
	s_add_u32 s30, s30, s43
	s_addc_u32 s31, s31, 0
	s_mov_b64 s[40:41], 0
	v_mov_b32_e32 v21, v193
	v_mov_b32_e32 v22, v189

; __device__ __forceinline__ int otid() { int t = threadIdx.x; asm volatile("" : "+v"(t)); return t; }
; template <int MODE>
; __device__ void phase_rmsnorm(const float* src, const float* __restrict__ w, u16* __restrict__ dstb, float* dstf) {
;   const int tid_ = otid();
;   const int lane = tid_ & 63;
;   const int gw = blockIdx.x * 4 + (tid_ >> 6);
;   const int nw = gridDim.x * 4;
;   float4 ww[4];
; #pragma unroll
;   for (int i = 0; i < 4; ++i) ww[i] = *(const float4*)(w + (i * 64 + lane) * 4);
;   float4 v[4], nv[4];
;   int row = gw;
;   if (row < TOK) {
; #pragma unroll
;     for (int i = 0; i < 4; ++i) v[i] = *(const float4*)(src + (size_t)row * DM + (i * 64 + lane) * 4);
;   }
;   while (row < TOK) {
;     const int nrow = row + nw;
;     if (nrow < TOK) {
; #pragma unroll
;       for (int i = 0; i < 4; ++i) nv[i] = *(const float4*)(src + (size_t)nrow * DM + (i * 64 + lane) * 4);
;     }
;     float ss = 0.f;
; #pragma unroll
;     for (int i = 0; i < 4; ++i) ss += v[i].x * v[i].x + v[i].y * v[i].y + v[i].z * v[i].z + v[i].w * v[i].w;
; #pragma unroll
;     for (int o = 1; o < 64; o <<= 1) ss += __shfl_xor(ss, o);
;     float rstd = rsqrtf(ss * (1.f / DM) + 1e-6f);
; #pragma unroll
;     for (int i = 0; i < 4; ++i) {
;       int c = (i * 64 + lane) * 4;
;       float a0 = v[i].x * rstd * ww[i].x, a1 = v[i].y * rstd * ww[i].y, a2 = v[i].z * rstd * ww[i].z, a3 = v[i].w * rstd * ww[i].w;
;       if (MODE == 0) {
;         uint2 o2; o2.x = pack2(a0, a1); o2.y = pack2(a2, a3);
;         *(uint2*)(dstb + (size_t)row * DM + c) = o2;
;       } else {
;         float4 o4; o4.x = a0; o4.y = a1; o4.z = a2; o4.w = a3;
;         *(float4*)(dstf + (size_t)row * DM + c) = o4;
;       }
;     }
.LBB0_350:
	s_andn2_b64 vcc, exec, s[0:1]
	s_cbranch_vccnz .LBB0_357
	v_mov_b32_e32 v30, v210
	v_readlane_b32 s0, v253, 5
	v_ashrrev_i32_e32 v0, 6, v30
	s_nop 0
	v_add_u32_e32 v50, s0, v0
	s_movk_i32 s0, 0x4000
	v_cmp_gt_i32_e32 vcc, s0, v50
	s_and_saveexec_b64 s[6:7], vcc
	s_cbranch_execz .LBB0_356
	v_readlane_b32 s0, v255, 21
	v_readlane_b32 s1, v255, 22
	s_lshl_b32 s0, s0, 10
	s_ashr_i32 s1, s0, 31
	v_readlane_b32 s56, v253, 38
	v_ashrrev_i32_e32 v51, 31, v50
	s_lshl_b64 s[0:1], s[0:1], 2
	v_readlane_b32 s58, v253, 40
	v_lshlrev_b32_e32 v0, 4, v30
	s_waitcnt vmcnt(17)
	v_lshlrev_b64 v[18:19], 12, v[50:51]
	v_readlane_b32 s59, v253, 41
	s_add_u32 s0, s58, s0
	v_and_b32_e32 v0, 0x3f0, v0
	v_lshl_add_u64 v[18:19], s[22:23], 0, v[18:19]
	s_addc_u32 s1, s59, s1
	v_lshl_add_u64 v[26:27], v[18:19], 0, v[0:1]
	v_readlane_b32 s38, v253, 3
	v_readlane_b32 s39, v253, 4
	s_load_dword s40, s[38:39], 0x0
	s_waitcnt lgkmcnt(0)
	s_cmpk_lg_u32 s40, 0x200
	s_cbranch_scc1 .Lrmsb_std
	global_load_dwordx4 v[2:5], v0, s[0:1]
	global_load_dwordx4 v[6:9], v0, s[0:1] offset:1024
	global_load_dwordx4 v[10:13], v0, s[0:1] offset:2048
	global_load_dwordx4 v[14:17], v0, s[0:1] offset:3072
	v_bfe_u32 v146, v50, 2, 3
	v_lshrrev_b32_e32 v147, 5, v50
	v_and_b32_e32 v148, 3, v50
	v_lshlrev_b32_e32 v146, 11, v146
	v_lshl_or_b32 v147, v147, 2, v148
	v_or_b32_e32 v146, v146, v147
	v_sub_u32_e32 v148, v146, v50
	v_mov_b32_e32 v147, 0
	v_ashrrev_i32_e32 v149, 31, v148
	v_lshlrev_b64 v[148:149], 12, v[148:149]
	v_lshl_add_u64 v[154:155], v[26:27], 0, v[148:149]
	s_mov_b32 s38, 0x100000
	s_mov_b32 s39, 0
	v_lshlrev_b64 v[156:157], 11, v[146:147]
	v_and_b32_e32 v158, 63, v210
	v_lshl_or_b32 v156, v158, 3, v156
	v_lshl_add_u64 v[156:157], s[36:37], 0, v[156:157]
	s_mov_b32 s40, 0x80000
	s_mov_b32 s41, 0
	global_load_dwordx4 v[18:21], v[154:155], off
	global_load_dwordx4 v[22:25], v[154:155], off offset:1024
	global_load_dwordx4 v[26:29], v[154:155], off offset:2048
	global_load_dwordx4 v[30:33], v[154:155], off offset:3072
	v_lshl_add_u64 v[154:155], v[154:155], 0, s[38:39]
	global_load_dwordx4 v[34:37], v[154:155], off
	global_load_dwordx4 v[38:41], v[154:155], off offset:1024
	global_load_dwordx4 v[42:45], v[154:155], off offset:2048
	global_load_dwordx4 v[46:49], v[154:155], off offset:3072
	v_lshl_add_u64 v[154:155], v[154:155], 0, s[38:39]
	global_load_dwordx4 v[50:53], v[154:155], off
	global_load_dwordx4 v[54:57], v[154:155], off offset:1024
	global_load_dwordx4 v[58:61], v[154:155], off offset:2048
	global_load_dwordx4 v[62:65], v[154:155], off offset:3072
	v_lshl_add_u64 v[154:155], v[154:155], 0, s[38:39]
	global_load_dwordx4 v[66:69], v[154:155], off
	global_load_dwordx4 v[70:73], v[154:155], off offset:1024
	global_load_dwordx4 v[74:77], v[154:155], off offset:2048
	global_load_dwordx4 v[78:81], v[154:155], off offset:3072
	v_lshl_add_u64 v[154:155], v[154:155], 0, s[38:39]
	global_load_dwordx4 v[82:85], v[154:155], off
	global_load_dwordx4 v[86:89], v[154:155], off offset:1024
	global_load_dwordx4 v[90:93], v[154:155], off offset:2048
	global_load_dwordx4 v[94:97], v[154:155], off offset:3072
	v_lshl_add_u64 v[154:155], v[154:155], 0, s[38:39]
	global_load_dwordx4 v[98:101], v[154:155], off
	global_load_dwordx4 v[102:105], v[154:155], off offset:1024
	global_load_dwordx4 v[106:109], v[154:155], off offset:2048
	global_load_dwordx4 v[110:113], v[154:155], off offset:3072
	v_lshl_add_u64 v[154:155], v[154:155], 0, s[38:39]
	global_load_dwordx4 v[114:117], v[154:155], off
	global_load_dwordx4 v[118:121], v[154:155], off offset:1024
	global_load_dwordx4 v[122:125], v[154:155], off offset:2048
	global_load_dwordx4 v[126:129], v[154:155], off offset:3072
	v_lshl_add_u64 v[154:155], v[154:155], 0, s[38:39]
	global_load_dwordx4 v[130:133], v[154:155], off
	global_load_dwordx4 v[134:137], v[154:155], off offset:1024
	global_load_dwordx4 v[138:141], v[154:155], off offset:2048
	global_load_dwordx4 v[142:145], v[154:155], off offset:3072
	s_waitcnt vmcnt(28)
	v_mul_f32_e32 v146, v22, v22
	v_mul_f32_e32 v147, v18, v18
	v_fmac_f32_e32 v146, v23, v23
	v_fmac_f32_e32 v147, v19, v19
	v_fmac_f32_e32 v146, v24, v24
	v_fmac_f32_e32 v147, v20, v20
	v_fmac_f32_e32 v146, v25, v25
	v_fmac_f32_e32 v147, v21, v21
	v_mul_f32_e32 v148, v30, v30
	v_mul_f32_e32 v149, v26, v26
	v_fmac_f32_e32 v148, v31, v31
	v_fmac_f32_e32 v149, v27, v27
	v_fmac_f32_e32 v148, v32, v32
	v_fmac_f32_e32 v149, v28, v28
	v_fmac_f32_e32 v148, v33, v33
	v_fmac_f32_e32 v149, v29, v29
	v_add_f32_e32 v150, v146, v147
	v_add_f32_e32 v150, v149, v150
	v_add_f32_e32 v150, v148, v150
	s_nop 1
	v_add_f32_dpp v150, v150, v150 quad_perm:[1,0,3,2] row_mask:0xf bank_mask:0xf
	s_nop 1
	v_add_f32_dpp v150, v150, v150 quad_perm:[2,3,0,1] row_mask:0xf bank_mask:0xf
	s_nop 1
	v_add_f32_dpp v150, v150, v150 row_half_mirror row_mask:0xf bank_mask:0xf
	s_nop 1
	v_add_f32_dpp v150, v150, v150 row_mirror row_mask:0xf bank_mask:0xf
	v_mov_b32_e32 v151, v150
	s_nop 1
	v_permlane16_swap_b32_e32 v150, v151
	s_nop 1
	v_add_f32_e32 v150, v150, v151
	v_mov_b32_e32 v151, v150
	s_nop 1
	v_permlane32_swap_b32_e32 v150, v151
	s_nop 1
	v_add_f32_e32 v150, v150, v151
	v_fmamk_f32 v150, v150, 0x3a800000, v211
	v_cmp_gt_f32_e32 vcc, 0x800000, v150
	v_mul_f32_e32 v151, 0x4b800000, v150
	s_nop 0
	v_cndmask_b32_e32 v150, v150, v151, vcc
	v_rsq_f32_e32 v150, v150
	s_nop 0
	v_mul_f32_e32 v151, 0x45800000, v150
	v_cndmask_b32_e32 v150, v150, v151, vcc
	v_mul_f32_e32 v18, v18, v150
	v_mul_f32_e32 v19, v19, v150
	v_mul_f32_e32 v20, v20, v150
	v_mul_f32_e32 v21, v21, v150
	v_mul_f32_e32 v18, v2, v18
	v_mul_f32_e32 v19, v3, v19
	v_mul_f32_e32 v20, v4, v20
	v_mul_f32_e32 v21, v5, v21
	v_cvt_pk_bf16_f32 v18, v18, v19
	v_cvt_pk_bf16_f32 v19, v20, v21
	global_store_dwordx2 v[156:157], v[18:19], off
	v_mul_f32_e32 v22, v22, v150
	v_mul_f32_e32 v23, v23, v150
	v_mul_f32_e32 v24, v24, v150
	v_mul_f32_e32 v25, v25, v150
	v_mul_f32_e32 v22, v6, v22
	v_mul_f32_e32 v23, v7, v23
	v_mul_f32_e32 v24, v8, v24
	v_mul_f32_e32 v25, v9, v25
	v_cvt_pk_bf16_f32 v22, v22, v23
	v_cvt_pk_bf16_f32 v23, v24, v25
	global_store_dwordx2 v[156:157], v[22:23], off offset:512
	v_mul_f32_e32 v26, v26, v150
	v_mul_f32_e32 v27, v27, v150
	v_mul_f32_e32 v28, v28, v150
	v_mul_f32_e32 v29, v29, v150
	v_mul_f32_e32 v26, v10, v26
	v_mul_f32_e32 v27, v11, v27
	v_mul_f32_e32 v28, v12, v28
	v_mul_f32_e32 v29, v13, v29
	v_cvt_pk_bf16_f32 v26, v26, v27
	v_cvt_pk_bf16_f32 v27, v28, v29
	global_store_dwordx2 v[156:157], v[26:27], off offset:1024
	v_mul_f32_e32 v30, v30, v150
	v_mul_f32_e32 v31, v31, v150
	v_mul_f32_e32 v32, v32, v150
	v_mul_f32_e32 v33, v33, v150
	v_mul_f32_e32 v30, v14, v30
	v_mul_f32_e32 v31, v15, v31
	v_mul_f32_e32 v32, v16, v32
	v_mul_f32_e32 v33, v17, v33
	v_cvt_pk_bf16_f32 v30, v30, v31
	v_cvt_pk_bf16_f32 v31, v32, v33
	global_store_dwordx2 v[156:157], v[30:31], off offset:1536
	v_lshl_add_u64 v[156:157], v[156:157], 0, s[40:41]
	s_waitcnt vmcnt(28)
; template <int MODE>
; __device__ void phase_rmsnorm(const float* src, const float* __restrict__ w, u16* __restrict__ dstb, float* dstf) {
;     ...
;     float ss = 0.f;
; #pragma unroll
;     for (int i = 0; i < 4; ++i) ss += v[i].x * v[i].x + v[i].y * v[i].y + v[i].z * v[i].z + v[i].w * v[i].w;
; #pragma unroll
;     for (int o = 1; o < 64; o <<= 1) ss += __shfl_xor(ss, o);
;     float rstd = rsqrtf(ss * (1.f / DM) + 1e-6f);
; #pragma unroll
;     for (int i = 0; i < 4; ++i) {
;       int c = (i * 64 + lane) * 4;
;       float a0 = v[i].x * rstd * ww[i].x, a1 = v[i].y * rstd * ww[i].y, a2 = v[i].z * rstd * ww[i].z, a3 = v[i].w * rstd * ww[i].w;
;       if (MODE == 0) {
;         uint2 o2; o2.x = pack2(a0, a1); o2.y = pack2(a2, a3);
;         *(uint2*)(dstb + (size_t)row * DM + c) = o2;
;       } else {
;         float4 o4; o4.x = a0; o4.y = a1; o4.z = a2; o4.w = a3;
;         *(float4*)(dstf + (size_t)row * DM + c) = o4;
;       }
;     }
	v_mul_f32_e32 v146, v38, v38
	v_mul_f32_e32 v147, v34, v34
	v_fmac_f32_e32 v146, v39, v39
	v_fmac_f32_e32 v147, v35, v35
	v_fmac_f32_e32 v146, v40, v40
	v_fmac_f32_e32 v147, v36, v36
	v_fmac_f32_e32 v146, v41, v41
	v_fmac_f32_e32 v147, v37, v37
	v_mul_f32_e32 v148, v46, v46
	v_mul_f32_e32 v149, v42, v42
	v_fmac_f32_e32 v148, v47, v47
	v_fmac_f32_e32 v149, v43, v43
	v_fmac_f32_e32 v148, v48, v48
	v_fmac_f32_e32 v149, v44, v44
	v_fmac_f32_e32 v148, v49, v49
	v_fmac_f32_e32 v149, v45, v45
	v_add_f32_e32 v150, v146, v147
	v_add_f32_e32 v150, v149, v150
	v_add_f32_e32 v150, v148, v150
	s_nop 1
	v_add_f32_dpp v150, v150, v150 quad_perm:[1,0,3,2] row_mask:0xf bank_mask:0xf
	s_nop 1
	v_add_f32_dpp v150, v150, v150 quad_perm:[2,3,0,1] row_mask:0xf bank_mask:0xf
	s_nop 1
	v_add_f32_dpp v150, v150, v150 row_half_mirror row_mask:0xf bank_mask:0xf
	s_nop 1
	v_add_f32_dpp v150, v150, v150 row_mirror row_mask:0xf bank_mask:0xf
	v_mov_b32_e32 v151, v150
	s_nop 1
	v_permlane16_swap_b32_e32 v150, v151
	s_nop 1
	v_add_f32_e32 v150, v150, v151
	v_mov_b32_e32 v151, v150
	s_nop 1
	v_permlane32_swap_b32_e32 v150, v151
	s_nop 1
	v_add_f32_e32 v150, v150, v151
	v_fmamk_f32 v150, v150, 0x3a800000, v211
	v_cmp_gt_f32_e32 vcc, 0x800000, v150
	v_mul_f32_e32 v151, 0x4b800000, v150
	s_nop 0
	v_cndmask_b32_e32 v150, v150, v151, vcc
	v_rsq_f32_e32 v150, v150
	s_nop 0
	v_mul_f32_e32 v151, 0x45800000, v150
	v_cndmask_b32_e32 v150, v150, v151, vcc
	v_mul_f32_e32 v34, v34, v150
	v_mul_f32_e32 v35, v35, v150
	v_mul_f32_e32 v36, v36, v150
	v_mul_f32_e32 v37, v37, v150
	v_mul_f32_e32 v34, v2, v34
	v_mul_f32_e32 v35, v3, v35
	v_mul_f32_e32 v36, v4, v36
	v_mul_f32_e32 v37, v5, v37
	v_cvt_pk_bf16_f32 v34, v34, v35
	v_cvt_pk_bf16_f32 v35, v36, v37
	global_store_dwordx2 v[156:157], v[34:35], off
	v_mul_f32_e32 v38, v38, v150
	v_mul_f32_e32 v39, v39, v150
	v_mul_f32_e32 v40, v40, v150
	v_mul_f32_e32 v41, v41, v150
	v_mul_f32_e32 v38, v6, v38
	v_mul_f32_e32 v39, v7, v39
	v_mul_f32_e32 v40, v8, v40
	v_mul_f32_e32 v41, v9, v41
	v_cvt_pk_bf16_f32 v38, v38, v39
	v_cvt_pk_bf16_f32 v39, v40, v41
	global_store_dwordx2 v[156:157], v[38:39], off offset:512
	v_mul_f32_e32 v42, v42, v150
	v_mul_f32_e32 v43, v43, v150
	v_mul_f32_e32 v44, v44, v150
	v_mul_f32_e32 v45, v45, v150
	v_mul_f32_e32 v42, v10, v42
	v_mul_f32_e32 v43, v11, v43
	v_mul_f32_e32 v44, v12, v44
	v_mul_f32_e32 v45, v13, v45
	v_cvt_pk_bf16_f32 v42, v42, v43
	v_cvt_pk_bf16_f32 v43, v44, v45
	global_store_dwordx2 v[156:157], v[42:43], off offset:1024
	v_mul_f32_e32 v46, v46, v150
	v_mul_f32_e32 v47, v47, v150
	v_mul_f32_e32 v48, v48, v150
	v_mul_f32_e32 v49, v49, v150
	v_mul_f32_e32 v46, v14, v46
	v_mul_f32_e32 v47, v15, v47
	v_mul_f32_e32 v48, v16, v48
	v_mul_f32_e32 v49, v17, v49
	v_cvt_pk_bf16_f32 v46, v46, v47
	v_cvt_pk_bf16_f32 v47, v48, v49
	global_store_dwordx2 v[156:157], v[46:47], off offset:1536
	v_lshl_add_u64 v[156:157], v[156:157], 0, s[40:41]
	s_waitcnt vmcnt(28)
	v_mul_f32_e32 v146, v54, v54
	v_mul_f32_e32 v147, v50, v50
	v_fmac_f32_e32 v146, v55, v55
	v_fmac_f32_e32 v147, v51, v51
	v_fmac_f32_e32 v146, v56, v56
	v_fmac_f32_e32 v147, v52, v52
	v_fmac_f32_e32 v146, v57, v57
	v_fmac_f32_e32 v147, v53, v53
	v_mul_f32_e32 v148, v62, v62
	v_mul_f32_e32 v149, v58, v58
	v_fmac_f32_e32 v148, v63, v63
	v_fmac_f32_e32 v149, v59, v59
	v_fmac_f32_e32 v148, v64, v64
	v_fmac_f32_e32 v149, v60, v60
	v_fmac_f32_e32 v148, v65, v65
	v_fmac_f32_e32 v149, v61, v61
	v_add_f32_e32 v150, v146, v147
	v_add_f32_e32 v150, v149, v150
	v_add_f32_e32 v150, v148, v150
	s_nop 1
	v_add_f32_dpp v150, v150, v150 quad_perm:[1,0,3,2] row_mask:0xf bank_mask:0xf
	s_nop 1
	v_add_f32_dpp v150, v150, v150 quad_perm:[2,3,0,1] row_mask:0xf bank_mask:0xf
	s_nop 1
	v_add_f32_dpp v150, v150, v150 row_half_mirror row_mask:0xf bank_mask:0xf
	s_nop 1
	v_add_f32_dpp v150, v150, v150 row_mirror row_mask:0xf bank_mask:0xf
	v_mov_b32_e32 v151, v150
	s_nop 1
	v_permlane16_swap_b32_e32 v150, v151
	s_nop 1
	v_add_f32_e32 v150, v150, v151
	v_mov_b32_e32 v151, v150
	s_nop 1
	v_permlane32_swap_b32_e32 v150, v151
	s_nop 1
	v_add_f32_e32 v150, v150, v151
	v_fmamk_f32 v150, v150, 0x3a800000, v211
	v_cmp_gt_f32_e32 vcc, 0x800000, v150
	v_mul_f32_e32 v151, 0x4b800000, v150
	s_nop 0
	v_cndmask_b32_e32 v150, v150, v151, vcc
	v_rsq_f32_e32 v150, v150
	s_nop 0
	v_mul_f32_e32 v151, 0x45800000, v150
	v_cndmask_b32_e32 v150, v150, v151, vcc
	v_mul_f32_e32 v50, v50, v150
	v_mul_f32_e32 v51, v51, v150
	v_mul_f32_e32 v52, v52, v150
	v_mul_f32_e32 v53, v53, v150
	v_mul_f32_e32 v50, v2, v50
	v_mul_f32_e32 v51, v3, v51
	v_mul_f32_e32 v52, v4, v52
	v_mul_f32_e32 v53, v5, v53
	v_cvt_pk_bf16_f32 v50, v50, v51
	v_cvt_pk_bf16_f32 v51, v52, v53
	global_store_dwordx2 v[156:157], v[50:51], off
	v_mul_f32_e32 v54, v54, v150
	v_mul_f32_e32 v55, v55, v150
	v_mul_f32_e32 v56, v56, v150
	v_mul_f32_e32 v57, v57, v150
	v_mul_f32_e32 v54, v6, v54
	v_mul_f32_e32 v55, v7, v55
	v_mul_f32_e32 v56, v8, v56
	v_mul_f32_e32 v57, v9, v57
	v_cvt_pk_bf16_f32 v54, v54, v55
	v_cvt_pk_bf16_f32 v55, v56, v57
	global_store_dwordx2 v[156:157], v[54:55], off offset:512
	v_mul_f32_e32 v58, v58, v150
	v_mul_f32_e32 v59, v59, v150
	v_mul_f32_e32 v60, v60, v150
	v_mul_f32_e32 v61, v61, v150
	v_mul_f32_e32 v58, v10, v58
	v_mul_f32_e32 v59, v11, v59
	v_mul_f32_e32 v60, v12, v60
	v_mul_f32_e32 v61, v13, v61
	v_cvt_pk_bf16_f32 v58, v58, v59
	v_cvt_pk_bf16_f32 v59, v60, v61
	global_store_dwordx2 v[156:157], v[58:59], off offset:1024
	v_mul_f32_e32 v62, v62, v150
	v_mul_f32_e32 v63, v63, v150
	v_mul_f32_e32 v64, v64, v150
	v_mul_f32_e32 v65, v65, v150
	v_mul_f32_e32 v62, v14, v62
	v_mul_f32_e32 v63, v15, v63
	v_mul_f32_e32 v64, v16, v64
	v_mul_f32_e32 v65, v17, v65
	v_cvt_pk_bf16_f32 v62, v62, v63
	v_cvt_pk_bf16_f32 v63, v64, v65
	global_store_dwordx2 v[156:157], v[62:63], off offset:1536
	v_lshl_add_u64 v[156:157], v[156:157], 0, s[40:41]
	s_waitcnt vmcnt(28)
; template <int MODE>
; __device__ void phase_rmsnorm(const float* src, const float* __restrict__ w, u16* __restrict__ dstb, float* dstf) {
;     ...
;     float ss = 0.f;
; #pragma unroll
;     for (int i = 0; i < 4; ++i) ss += v[i].x * v[i].x + v[i].y * v[i].y + v[i].z * v[i].z + v[i].w * v[i].w;
; #pragma unroll
;     for (int o = 1; o < 64; o <<= 1) ss += __shfl_xor(ss, o);
;     float rstd = rsqrtf(ss * (1.f / DM) + 1e-6f);
; #pragma unroll
;     for (int i = 0; i < 4; ++i) {
;       int c = (i * 64 + lane) * 4;
;       float a0 = v[i].x * rstd * ww[i].x, a1 = v[i].y * rstd * ww[i].y, a2 = v[i].z * rstd * ww[i].z, a3 = v[i].w * rstd * ww[i].w;
;       if (MODE == 0) {
;         uint2 o2; o2.x = pack2(a0, a1); o2.y = pack2(a2, a3);
;         *(uint2*)(dstb + (size_t)row * DM + c) = o2;
;       } else {
;         float4 o4; o4.x = a0; o4.y = a1; o4.z = a2; o4.w = a3;
;         *(float4*)(dstf + (size_t)row * DM + c) = o4;
;       }
;     }
	v_mul_f32_e32 v146, v70, v70
	v_mul_f32_e32 v147, v66, v66
	v_fmac_f32_e32 v146, v71, v71
	v_fmac_f32_e32 v147, v67, v67
	v_fmac_f32_e32 v146, v72, v72
	v_fmac_f32_e32 v147, v68, v68
	v_fmac_f32_e32 v146, v73, v73
	v_fmac_f32_e32 v147, v69, v69
	v_mul_f32_e32 v148, v78, v78
	v_mul_f32_e32 v149, v74, v74
	v_fmac_f32_e32 v148, v79, v79
	v_fmac_f32_e32 v149, v75, v75
	v_fmac_f32_e32 v148, v80, v80
	v_fmac_f32_e32 v149, v76, v76
	v_fmac_f32_e32 v148, v81, v81
	v_fmac_f32_e32 v149, v77, v77
	v_add_f32_e32 v150, v146, v147
	v_add_f32_e32 v150, v149, v150
	v_add_f32_e32 v150, v148, v150
	s_nop 1
	v_add_f32_dpp v150, v150, v150 quad_perm:[1,0,3,2] row_mask:0xf bank_mask:0xf
	s_nop 1
	v_add_f32_dpp v150, v150, v150 quad_perm:[2,3,0,1] row_mask:0xf bank_mask:0xf
	s_nop 1
	v_add_f32_dpp v150, v150, v150 row_half_mirror row_mask:0xf bank_mask:0xf
	s_nop 1
	v_add_f32_dpp v150, v150, v150 row_mirror row_mask:0xf bank_mask:0xf
	v_mov_b32_e32 v151, v150
	s_nop 1
	v_permlane16_swap_b32_e32 v150, v151
	s_nop 1
	v_add_f32_e32 v150, v150, v151
	v_mov_b32_e32 v151, v150
	s_nop 1
	v_permlane32_swap_b32_e32 v150, v151
	s_nop 1
	v_add_f32_e32 v150, v150, v151
	v_fmamk_f32 v150, v150, 0x3a800000, v211
	v_cmp_gt_f32_e32 vcc, 0x800000, v150
	v_mul_f32_e32 v151, 0x4b800000, v150
	s_nop 0
	v_cndmask_b32_e32 v150, v150, v151, vcc
	v_rsq_f32_e32 v150, v150
	s_nop 0
	v_mul_f32_e32 v151, 0x45800000, v150
	v_cndmask_b32_e32 v150, v150, v151, vcc
	v_mul_f32_e32 v66, v66, v150
	v_mul_f32_e32 v67, v67, v150
	v_mul_f32_e32 v68, v68, v150
	v_mul_f32_e32 v69, v69, v150
	v_mul_f32_e32 v66, v2, v66
	v_mul_f32_e32 v67, v3, v67
	v_mul_f32_e32 v68, v4, v68
	v_mul_f32_e32 v69, v5, v69
	v_cvt_pk_bf16_f32 v66, v66, v67
	v_cvt_pk_bf16_f32 v67, v68, v69
	global_store_dwordx2 v[156:157], v[66:67], off
	v_mul_f32_e32 v70, v70, v150
	v_mul_f32_e32 v71, v71, v150
	v_mul_f32_e32 v72, v72, v150
	v_mul_f32_e32 v73, v73, v150
	v_mul_f32_e32 v70, v6, v70
	v_mul_f32_e32 v71, v7, v71
	v_mul_f32_e32 v72, v8, v72
	v_mul_f32_e32 v73, v9, v73
	v_cvt_pk_bf16_f32 v70, v70, v71
	v_cvt_pk_bf16_f32 v71, v72, v73
	global_store_dwordx2 v[156:157], v[70:71], off offset:512
	v_mul_f32_e32 v74, v74, v150
	v_mul_f32_e32 v75, v75, v150
	v_mul_f32_e32 v76, v76, v150
	v_mul_f32_e32 v77, v77, v150
	v_mul_f32_e32 v74, v10, v74
	v_mul_f32_e32 v75, v11, v75
	v_mul_f32_e32 v76, v12, v76
	v_mul_f32_e32 v77, v13, v77
	v_cvt_pk_bf16_f32 v74, v74, v75
	v_cvt_pk_bf16_f32 v75, v76, v77
	global_store_dwordx2 v[156:157], v[74:75], off offset:1024
	v_mul_f32_e32 v78, v78, v150
	v_mul_f32_e32 v79, v79, v150
	v_mul_f32_e32 v80, v80, v150
	v_mul_f32_e32 v81, v81, v150
	v_mul_f32_e32 v78, v14, v78
	v_mul_f32_e32 v79, v15, v79
	v_mul_f32_e32 v80, v16, v80
	v_mul_f32_e32 v81, v17, v81
	v_cvt_pk_bf16_f32 v78, v78, v79
	v_cvt_pk_bf16_f32 v79, v80, v81
	global_store_dwordx2 v[156:157], v[78:79], off offset:1536
	v_lshl_add_u64 v[156:157], v[156:157], 0, s[40:41]
	s_waitcnt vmcnt(28)
	v_mul_f32_e32 v146, v86, v86
	v_mul_f32_e32 v147, v82, v82
	v_fmac_f32_e32 v146, v87, v87
	v_fmac_f32_e32 v147, v83, v83
	v_fmac_f32_e32 v146, v88, v88
	v_fmac_f32_e32 v147, v84, v84
	v_fmac_f32_e32 v146, v89, v89
	v_fmac_f32_e32 v147, v85, v85
	v_mul_f32_e32 v148, v94, v94
	v_mul_f32_e32 v149, v90, v90
	v_fmac_f32_e32 v148, v95, v95
	v_fmac_f32_e32 v149, v91, v91
	v_fmac_f32_e32 v148, v96, v96
	v_fmac_f32_e32 v149, v92, v92
	v_fmac_f32_e32 v148, v97, v97
	v_fmac_f32_e32 v149, v93, v93
	v_add_f32_e32 v150, v146, v147
	v_add_f32_e32 v150, v149, v150
	v_add_f32_e32 v150, v148, v150
	s_nop 1
	v_add_f32_dpp v150, v150, v150 quad_perm:[1,0,3,2] row_mask:0xf bank_mask:0xf
	s_nop 1
	v_add_f32_dpp v150, v150, v150 quad_perm:[2,3,0,1] row_mask:0xf bank_mask:0xf
	s_nop 1
	v_add_f32_dpp v150, v150, v150 row_half_mirror row_mask:0xf bank_mask:0xf
	s_nop 1
	v_add_f32_dpp v150, v150, v150 row_mirror row_mask:0xf bank_mask:0xf
	v_mov_b32_e32 v151, v150
	s_nop 1
	v_permlane16_swap_b32_e32 v150, v151
	s_nop 1
	v_add_f32_e32 v150, v150, v151
	v_mov_b32_e32 v151, v150
	s_nop 1
	v_permlane32_swap_b32_e32 v150, v151
	s_nop 1
	v_add_f32_e32 v150, v150, v151
	v_fmamk_f32 v150, v150, 0x3a800000, v211
	v_cmp_gt_f32_e32 vcc, 0x800000, v150
	v_mul_f32_e32 v151, 0x4b800000, v150
	s_nop 0
	v_cndmask_b32_e32 v150, v150, v151, vcc
	v_rsq_f32_e32 v150, v150
	s_nop 0
	v_mul_f32_e32 v151, 0x45800000, v150
	v_cndmask_b32_e32 v150, v150, v151, vcc
	v_mul_f32_e32 v82, v82, v150
	v_mul_f32_e32 v83, v83, v150
	v_mul_f32_e32 v84, v84, v150
	v_mul_f32_e32 v85, v85, v150
	v_mul_f32_e32 v82, v2, v82
	v_mul_f32_e32 v83, v3, v83
	v_mul_f32_e32 v84, v4, v84
	v_mul_f32_e32 v85, v5, v85
	v_cvt_pk_bf16_f32 v82, v82, v83
	v_cvt_pk_bf16_f32 v83, v84, v85
	global_store_dwordx2 v[156:157], v[82:83], off
	v_mul_f32_e32 v86, v86, v150
	v_mul_f32_e32 v87, v87, v150
	v_mul_f32_e32 v88, v88, v150
	v_mul_f32_e32 v89, v89, v150
	v_mul_f32_e32 v86, v6, v86
	v_mul_f32_e32 v87, v7, v87
	v_mul_f32_e32 v88, v8, v88
	v_mul_f32_e32 v89, v9, v89
	v_cvt_pk_bf16_f32 v86, v86, v87
	v_cvt_pk_bf16_f32 v87, v88, v89
	global_store_dwordx2 v[156:157], v[86:87], off offset:512
	v_mul_f32_e32 v90, v90, v150
	v_mul_f32_e32 v91, v91, v150
	v_mul_f32_e32 v92, v92, v150
	v_mul_f32_e32 v93, v93, v150
	v_mul_f32_e32 v90, v10, v90
	v_mul_f32_e32 v91, v11, v91
	v_mul_f32_e32 v92, v12, v92
	v_mul_f32_e32 v93, v13, v93
	v_cvt_pk_bf16_f32 v90, v90, v91
	v_cvt_pk_bf16_f32 v91, v92, v93
	global_store_dwordx2 v[156:157], v[90:91], off offset:1024
	v_mul_f32_e32 v94, v94, v150
	v_mul_f32_e32 v95, v95, v150
	v_mul_f32_e32 v96, v96, v150
	v_mul_f32_e32 v97, v97, v150
	v_mul_f32_e32 v94, v14, v94
	v_mul_f32_e32 v95, v15, v95
	v_mul_f32_e32 v96, v16, v96
	v_mul_f32_e32 v97, v17, v97
	v_cvt_pk_bf16_f32 v94, v94, v95
	v_cvt_pk_bf16_f32 v95, v96, v97
	global_store_dwordx2 v[156:157], v[94:95], off offset:1536
	v_lshl_add_u64 v[156:157], v[156:157], 0, s[40:41]
	s_waitcnt vmcnt(28)
; template <int MODE>
; __device__ void phase_rmsnorm(const float* src, const float* __restrict__ w, u16* __restrict__ dstb, float* dstf) {
;     ...
;     float ss = 0.f;
; #pragma unroll
;     for (int i = 0; i < 4; ++i) ss += v[i].x * v[i].x + v[i].y * v[i].y + v[i].z * v[i].z + v[i].w * v[i].w;
; #pragma unroll
;     for (int o = 1; o < 64; o <<= 1) ss += __shfl_xor(ss, o);
;     float rstd = rsqrtf(ss * (1.f / DM) + 1e-6f);
; #pragma unroll
;     for (int i = 0; i < 4; ++i) {
;       int c = (i * 64 + lane) * 4;
;       float a0 = v[i].x * rstd * ww[i].x, a1 = v[i].y * rstd * ww[i].y, a2 = v[i].z * rstd * ww[i].z, a3 = v[i].w * rstd * ww[i].w;
;       if (MODE == 0) {
;         uint2 o2; o2.x = pack2(a0, a1); o2.y = pack2(a2, a3);
;         *(uint2*)(dstb + (size_t)row * DM + c) = o2;
;       } else {
;         float4 o4; o4.x = a0; o4.y = a1; o4.z = a2; o4.w = a3;
;         *(float4*)(dstf + (size_t)row * DM + c) = o4;
;       }
;     }
	v_mul_f32_e32 v146, v102, v102
	v_mul_f32_e32 v147, v98, v98
	v_fmac_f32_e32 v146, v103, v103
	v_fmac_f32_e32 v147, v99, v99
	v_fmac_f32_e32 v146, v104, v104
	v_fmac_f32_e32 v147, v100, v100
	v_fmac_f32_e32 v146, v105, v105
	v_fmac_f32_e32 v147, v101, v101
	v_mul_f32_e32 v148, v110, v110
	v_mul_f32_e32 v149, v106, v106
	v_fmac_f32_e32 v148, v111, v111
	v_fmac_f32_e32 v149, v107, v107
	v_fmac_f32_e32 v148, v112, v112
	v_fmac_f32_e32 v149, v108, v108
	v_fmac_f32_e32 v148, v113, v113
	v_fmac_f32_e32 v149, v109, v109
	v_add_f32_e32 v150, v146, v147
	v_add_f32_e32 v150, v149, v150
	v_add_f32_e32 v150, v148, v150
	s_nop 1
	v_add_f32_dpp v150, v150, v150 quad_perm:[1,0,3,2] row_mask:0xf bank_mask:0xf
	s_nop 1
	v_add_f32_dpp v150, v150, v150 quad_perm:[2,3,0,1] row_mask:0xf bank_mask:0xf
	s_nop 1
	v_add_f32_dpp v150, v150, v150 row_half_mirror row_mask:0xf bank_mask:0xf
	s_nop 1
	v_add_f32_dpp v150, v150, v150 row_mirror row_mask:0xf bank_mask:0xf
	v_mov_b32_e32 v151, v150
	s_nop 1
	v_permlane16_swap_b32_e32 v150, v151
	s_nop 1
	v_add_f32_e32 v150, v150, v151
	v_mov_b32_e32 v151, v150
	s_nop 1
	v_permlane32_swap_b32_e32 v150, v151
	s_nop 1
	v_add_f32_e32 v150, v150, v151
	v_fmamk_f32 v150, v150, 0x3a800000, v211
	v_cmp_gt_f32_e32 vcc, 0x800000, v150
	v_mul_f32_e32 v151, 0x4b800000, v150
	s_nop 0
	v_cndmask_b32_e32 v150, v150, v151, vcc
	v_rsq_f32_e32 v150, v150
	s_nop 0
	v_mul_f32_e32 v151, 0x45800000, v150
	v_cndmask_b32_e32 v150, v150, v151, vcc
	v_mul_f32_e32 v98, v98, v150
	v_mul_f32_e32 v99, v99, v150
	v_mul_f32_e32 v100, v100, v150
	v_mul_f32_e32 v101, v101, v150
	v_mul_f32_e32 v98, v2, v98
	v_mul_f32_e32 v99, v3, v99
	v_mul_f32_e32 v100, v4, v100
	v_mul_f32_e32 v101, v5, v101
	v_cvt_pk_bf16_f32 v98, v98, v99
	v_cvt_pk_bf16_f32 v99, v100, v101
	global_store_dwordx2 v[156:157], v[98:99], off
	v_mul_f32_e32 v102, v102, v150
	v_mul_f32_e32 v103, v103, v150
	v_mul_f32_e32 v104, v104, v150
	v_mul_f32_e32 v105, v105, v150
	v_mul_f32_e32 v102, v6, v102
	v_mul_f32_e32 v103, v7, v103
	v_mul_f32_e32 v104, v8, v104
	v_mul_f32_e32 v105, v9, v105
	v_cvt_pk_bf16_f32 v102, v102, v103
	v_cvt_pk_bf16_f32 v103, v104, v105
	global_store_dwordx2 v[156:157], v[102:103], off offset:512
	v_mul_f32_e32 v106, v106, v150
	v_mul_f32_e32 v107, v107, v150
	v_mul_f32_e32 v108, v108, v150
	v_mul_f32_e32 v109, v109, v150
	v_mul_f32_e32 v106, v10, v106
	v_mul_f32_e32 v107, v11, v107
	v_mul_f32_e32 v108, v12, v108
	v_mul_f32_e32 v109, v13, v109
	v_cvt_pk_bf16_f32 v106, v106, v107
	v_cvt_pk_bf16_f32 v107, v108, v109
	global_store_dwordx2 v[156:157], v[106:107], off offset:1024
	v_mul_f32_e32 v110, v110, v150
	v_mul_f32_e32 v111, v111, v150
	v_mul_f32_e32 v112, v112, v150
	v_mul_f32_e32 v113, v113, v150
	v_mul_f32_e32 v110, v14, v110
	v_mul_f32_e32 v111, v15, v111
	v_mul_f32_e32 v112, v16, v112
	v_mul_f32_e32 v113, v17, v113
	v_cvt_pk_bf16_f32 v110, v110, v111
	v_cvt_pk_bf16_f32 v111, v112, v113
	global_store_dwordx2 v[156:157], v[110:111], off offset:1536
	v_lshl_add_u64 v[156:157], v[156:157], 0, s[40:41]
	s_waitcnt vmcnt(28)
	v_mul_f32_e32 v146, v118, v118
	v_mul_f32_e32 v147, v114, v114
	v_fmac_f32_e32 v146, v119, v119
	v_fmac_f32_e32 v147, v115, v115
	v_fmac_f32_e32 v146, v120, v120
	v_fmac_f32_e32 v147, v116, v116
	v_fmac_f32_e32 v146, v121, v121
	v_fmac_f32_e32 v147, v117, v117
	v_mul_f32_e32 v148, v126, v126
	v_mul_f32_e32 v149, v122, v122
	v_fmac_f32_e32 v148, v127, v127
	v_fmac_f32_e32 v149, v123, v123
	v_fmac_f32_e32 v148, v128, v128
	v_fmac_f32_e32 v149, v124, v124
	v_fmac_f32_e32 v148, v129, v129
	v_fmac_f32_e32 v149, v125, v125
	v_add_f32_e32 v150, v146, v147
	v_add_f32_e32 v150, v149, v150
	v_add_f32_e32 v150, v148, v150
	s_nop 1
	v_add_f32_dpp v150, v150, v150 quad_perm:[1,0,3,2] row_mask:0xf bank_mask:0xf
	s_nop 1
	v_add_f32_dpp v150, v150, v150 quad_perm:[2,3,0,1] row_mask:0xf bank_mask:0xf
	s_nop 1
	v_add_f32_dpp v150, v150, v150 row_half_mirror row_mask:0xf bank_mask:0xf
	s_nop 1
	v_add_f32_dpp v150, v150, v150 row_mirror row_mask:0xf bank_mask:0xf
	v_mov_b32_e32 v151, v150
	s_nop 1
	v_permlane16_swap_b32_e32 v150, v151
	s_nop 1
	v_add_f32_e32 v150, v150, v151
	v_mov_b32_e32 v151, v150
	s_nop 1
	v_permlane32_swap_b32_e32 v150, v151
	s_nop 1
	v_add_f32_e32 v150, v150, v151
	v_fmamk_f32 v150, v150, 0x3a800000, v211
	v_cmp_gt_f32_e32 vcc, 0x800000, v150
	v_mul_f32_e32 v151, 0x4b800000, v150
	s_nop 0
	v_cndmask_b32_e32 v150, v150, v151, vcc
	v_rsq_f32_e32 v150, v150
	s_nop 0
	v_mul_f32_e32 v151, 0x45800000, v150
	v_cndmask_b32_e32 v150, v150, v151, vcc
	v_mul_f32_e32 v114, v114, v150
	v_mul_f32_e32 v115, v115, v150
	v_mul_f32_e32 v116, v116, v150
	v_mul_f32_e32 v117, v117, v150
	v_mul_f32_e32 v114, v2, v114
	v_mul_f32_e32 v115, v3, v115
	v_mul_f32_e32 v116, v4, v116
	v_mul_f32_e32 v117, v5, v117
	v_cvt_pk_bf16_f32 v114, v114, v115
	v_cvt_pk_bf16_f32 v115, v116, v117
	global_store_dwordx2 v[156:157], v[114:115], off
	v_mul_f32_e32 v118, v118, v150
	v_mul_f32_e32 v119, v119, v150
	v_mul_f32_e32 v120, v120, v150
	v_mul_f32_e32 v121, v121, v150
	v_mul_f32_e32 v118, v6, v118
	v_mul_f32_e32 v119, v7, v119
	v_mul_f32_e32 v120, v8, v120
	v_mul_f32_e32 v121, v9, v121
	v_cvt_pk_bf16_f32 v118, v118, v119
	v_cvt_pk_bf16_f32 v119, v120, v121
	global_store_dwordx2 v[156:157], v[118:119], off offset:512
	v_mul_f32_e32 v122, v122, v150
	v_mul_f32_e32 v123, v123, v150
	v_mul_f32_e32 v124, v124, v150
	v_mul_f32_e32 v125, v125, v150
	v_mul_f32_e32 v122, v10, v122
	v_mul_f32_e32 v123, v11, v123
	v_mul_f32_e32 v124, v12, v124
	v_mul_f32_e32 v125, v13, v125
	v_cvt_pk_bf16_f32 v122, v122, v123
	v_cvt_pk_bf16_f32 v123, v124, v125
	global_store_dwordx2 v[156:157], v[122:123], off offset:1024
	v_mul_f32_e32 v126, v126, v150
	v_mul_f32_e32 v127, v127, v150
	v_mul_f32_e32 v128, v128, v150
	v_mul_f32_e32 v129, v129, v150
	v_mul_f32_e32 v126, v14, v126
	v_mul_f32_e32 v127, v15, v127
	v_mul_f32_e32 v128, v16, v128
	v_mul_f32_e32 v129, v17, v129
	v_cvt_pk_bf16_f32 v126, v126, v127
	v_cvt_pk_bf16_f32 v127, v128, v129
	global_store_dwordx2 v[156:157], v[126:127], off offset:1536
	v_lshl_add_u64 v[156:157], v[156:157], 0, s[40:41]
	s_waitcnt vmcnt(28)
; __device__ __forceinline__ int otid() { int t = threadIdx.x; asm volatile("" : "+v"(t)); return t; }
; template <int MODE>
; __device__ void phase_rmsnorm(const float* src, const float* __restrict__ w, u16* __restrict__ dstb, float* dstf) {
;   const int tid_ = otid();
;   const int lane = tid_ & 63;
;   const int gw = blockIdx.x * 4 + (tid_ >> 6);
;   const int nw = gridDim.x * 4;
;   float4 ww[4];
; #pragma unroll
;   for (int i = 0; i < 4; ++i) ww[i] = *(const float4*)(w + (i * 64 + lane) * 4);
;   float4 v[4], nv[4];
;   int row = gw;
;   if (row < TOK) {
; #pragma unroll
;     for (int i = 0; i < 4; ++i) v[i] = *(const float4*)(src + (size_t)row * DM + (i * 64 + lane) * 4);
;   }
;   while (row < TOK) {
;     const int nrow = row + nw;
;     if (nrow < TOK) {
; #pragma unroll
;       for (int i = 0; i < 4; ++i) nv[i] = *(const float4*)(src + (size_t)nrow * DM + (i * 64 + lane) * 4);
;     }
;     float ss = 0.f;
; #pragma unroll
;     for (int i = 0; i < 4; ++i) ss += v[i].x * v[i].x + v[i].y * v[i].y + v[i].z * v[i].z + v[i].w * v[i].w;
; #pragma unroll
;     for (int o = 1; o < 64; o <<= 1) ss += __shfl_xor(ss, o);
;     float rstd = rsqrtf(ss * (1.f / DM) + 1e-6f);
; #pragma unroll
;     for (int i = 0; i < 4; ++i) {
;       int c = (i * 64 + lane) * 4;
;       float a0 = v[i].x * rstd * ww[i].x, a1 = v[i].y * rstd * ww[i].y, a2 = v[i].z * rstd * ww[i].z, a3 = v[i].w * rstd * ww[i].w;
;       if (MODE == 0) {
;         uint2 o2; o2.x = pack2(a0, a1); o2.y = pack2(a2, a3);
;         *(uint2*)(dstb + (size_t)row * DM + c) = o2;
;       } else {
;         float4 o4; o4.x = a0; o4.y = a1; o4.z = a2; o4.w = a3;
;         *(float4*)(dstf + (size_t)row * DM + c) = o4;
;       }
;     }
	v_mul_f32_e32 v146, v134, v134
	v_mul_f32_e32 v147, v130, v130
	v_fmac_f32_e32 v146, v135, v135
	v_fmac_f32_e32 v147, v131, v131
	v_fmac_f32_e32 v146, v136, v136
	v_fmac_f32_e32 v147, v132, v132
	v_fmac_f32_e32 v146, v137, v137
	v_fmac_f32_e32 v147, v133, v133
	v_mul_f32_e32 v148, v142, v142
	v_mul_f32_e32 v149, v138, v138
	v_fmac_f32_e32 v148, v143, v143
	v_fmac_f32_e32 v149, v139, v139
	v_fmac_f32_e32 v148, v144, v144
	v_fmac_f32_e32 v149, v140, v140
	v_fmac_f32_e32 v148, v145, v145
	v_fmac_f32_e32 v149, v141, v141
	v_add_f32_e32 v150, v146, v147
	v_add_f32_e32 v150, v149, v150
	v_add_f32_e32 v150, v148, v150
	s_nop 1
	v_add_f32_dpp v150, v150, v150 quad_perm:[1,0,3,2] row_mask:0xf bank_mask:0xf
	s_nop 1
	v_add_f32_dpp v150, v150, v150 quad_perm:[2,3,0,1] row_mask:0xf bank_mask:0xf
	s_nop 1
	v_add_f32_dpp v150, v150, v150 row_half_mirror row_mask:0xf bank_mask:0xf
	s_nop 1
	v_add_f32_dpp v150, v150, v150 row_mirror row_mask:0xf bank_mask:0xf
	v_mov_b32_e32 v151, v150
	s_nop 1
	v_permlane16_swap_b32_e32 v150, v151
	s_nop 1
	v_add_f32_e32 v150, v150, v151
	v_mov_b32_e32 v151, v150
	s_nop 1
	v_permlane32_swap_b32_e32 v150, v151
	s_nop 1
	v_add_f32_e32 v150, v150, v151
	v_fmamk_f32 v150, v150, 0x3a800000, v211
	v_cmp_gt_f32_e32 vcc, 0x800000, v150
	v_mul_f32_e32 v151, 0x4b800000, v150
	s_nop 0
	v_cndmask_b32_e32 v150, v150, v151, vcc
	v_rsq_f32_e32 v150, v150
	s_nop 0
	v_mul_f32_e32 v151, 0x45800000, v150
	v_cndmask_b32_e32 v150, v150, v151, vcc
	v_mul_f32_e32 v130, v130, v150
	v_mul_f32_e32 v131, v131, v150
	v_mul_f32_e32 v132, v132, v150
	v_mul_f32_e32 v133, v133, v150
	v_mul_f32_e32 v130, v2, v130
	v_mul_f32_e32 v131, v3, v131
	v_mul_f32_e32 v132, v4, v132
	v_mul_f32_e32 v133, v5, v133
	v_cvt_pk_bf16_f32 v130, v130, v131
	v_cvt_pk_bf16_f32 v131, v132, v133
	global_store_dwordx2 v[156:157], v[130:131], off
	v_mul_f32_e32 v134, v134, v150
	v_mul_f32_e32 v135, v135, v150
	v_mul_f32_e32 v136, v136, v150
	v_mul_f32_e32 v137, v137, v150
	v_mul_f32_e32 v134, v6, v134
	v_mul_f32_e32 v135, v7, v135
	v_mul_f32_e32 v136, v8, v136
	v_mul_f32_e32 v137, v9, v137
	v_cvt_pk_bf16_f32 v134, v134, v135
	v_cvt_pk_bf16_f32 v135, v136, v137
	global_store_dwordx2 v[156:157], v[134:135], off offset:512
	v_mul_f32_e32 v138, v138, v150
	v_mul_f32_e32 v139, v139, v150
	v_mul_f32_e32 v140, v140, v150
	v_mul_f32_e32 v141, v141, v150
	v_mul_f32_e32 v138, v10, v138
	v_mul_f32_e32 v139, v11, v139
	v_mul_f32_e32 v140, v12, v140
	v_mul_f32_e32 v141, v13, v141
	v_cvt_pk_bf16_f32 v138, v138, v139
	v_cvt_pk_bf16_f32 v139, v140, v141
	global_store_dwordx2 v[156:157], v[138:139], off offset:1024
	v_mul_f32_e32 v142, v142, v150
	v_mul_f32_e32 v143, v143, v150
	v_mul_f32_e32 v144, v144, v150
	v_mul_f32_e32 v145, v145, v150
	v_mul_f32_e32 v142, v14, v142
	v_mul_f32_e32 v143, v15, v143
	v_mul_f32_e32 v144, v16, v144
	v_mul_f32_e32 v145, v17, v145
	v_cvt_pk_bf16_f32 v142, v142, v143
	v_cvt_pk_bf16_f32 v143, v144, v145
	global_store_dwordx2 v[156:157], v[142:143], off offset:1536
	s_branch .LBB0_356
.Lrmsb_std:
	global_load_dwordx4 v[2:5], v0, s[0:1]
	global_load_dwordx4 v[6:9], v0, s[0:1] offset:1024
	global_load_dwordx4 v[10:13], v0, s[0:1] offset:2048
	global_load_dwordx4 v[14:17], v0, s[0:1] offset:3072
	global_load_dwordx4 v[34:37], v[26:27], off
	global_load_dwordx4 v[18:21], v[26:27], off offset:1024
	global_load_dwordx4 v[22:25], v[26:27], off offset:2048
	s_nop 0
	global_load_dwordx4 v[26:29], v[26:27], off offset:3072
	v_readlane_b32 s0, v253, 3
	v_cmp_lt_i32_e32 vcc, v250, v217
	v_readlane_b32 s1, v253, 4
	s_load_dword s0, s[0:1], 0x0
	v_cndmask_b32_e32 v0, v215, v250, vcc
	v_cmp_lt_i32_e32 vcc, v251, v217
	v_and_b32_e32 v38, 63, v30
	v_lshlrev_b64 v[32:33], 11, v[50:51]
	v_cndmask_b32_e32 v31, v215, v251, vcc
	v_cmp_lt_i32_e32 vcc, v252, v217
	v_lshlrev_b32_e32 v56, 2, v31
	s_waitcnt lgkmcnt(0)
	s_lshl_b32 s8, s0, 2
	v_cndmask_b32_e32 v31, v215, v252, vcc
	v_lshlrev_b32_e32 v57, 2, v31
	v_xor_b32_e32 v31, 8, v215
	v_cmp_lt_i32_e32 vcc, v31, v217
	v_add_u32_e32 v30, s8, v50
	v_lshl_or_b32 v32, v38, 3, v32
	v_cndmask_b32_e32 v31, v215, v31, vcc
	v_cmp_lt_i32_e32 vcc, v214, v217
	v_lshlrev_b32_e32 v58, 2, v31
	s_ashr_i32 s9, s8, 31
	v_cndmask_b32_e32 v31, v215, v214, vcc
	v_cmp_lt_i32_e32 vcc, v229, v217
	v_lshlrev_b32_e32 v59, 2, v31
	v_lshlrev_b32_e32 v0, 2, v0
	v_cndmask_b32_e32 v31, v215, v229, vcc
	v_lshlrev_b32_e32 v60, 2, v31
	v_ashrrev_i32_e32 v31, 31, v30
	v_lshlrev_b64 v[30:31], 12, v[30:31]
	v_lshl_or_b32 v30, v38, 4, v30
	v_lshl_add_u64 v[52:53], s[36:37], 0, v[32:33]
	s_lshl_b64 s[18:19], s[8:9], 11
	v_lshl_add_u64 v[54:55], s[22:23], 0, v[30:31]
	s_lshl_b64 s[24:25], s[8:9], 12
	s_mov_b64 s[30:31], 0
	v_readlane_b32 s57, v253, 39
	v_readlane_b32 s60, v253, 42
	v_readlane_b32 s61, v253, 43
	v_readlane_b32 s62, v253, 44
	v_readlane_b32 s63, v253, 45
	v_readlane_b32 s64, v253, 46
	v_readlane_b32 s65, v253, 47
	v_readlane_b32 s66, v253, 48
	v_readlane_b32 s67, v253, 49
	v_readlane_b32 s68, v253, 50
	v_readlane_b32 s69, v253, 51
	v_readlane_b32 s70, v253, 52
	v_readlane_b32 s71, v253, 53
	s_branch .LBB0_354

; __device__ __forceinline__ int otid() { int t = threadIdx.x; asm volatile("" : "+v"(t)); return t; }
; __device__ void phase_setup(const Params& p, unsigned char* smem) {
;     ...
;   const int lt_ = otid();
;   if (blockIdx.x == 0 && lt_ < DEPTH) {
;     int l = lt_;
;     float s1 = 0.f, s2 = 0.f;
;     for (int i = 0; i < 32; ++i) {
;       s1 += p.lq1[l * 32 + i] * p.lk1[l * 32 + i];
;       s2 += p.lq2[l * 32 + i] * p.lk2[l * 32 + i];
;     }
;     float lam_init = 0.8f - 0.6f * expf(-0.3f * (float)l);
;     P_LAM[l] = expf(s1) - expf(s2) + lam_init;
;   }
; }
; template <int MODE>
; __device__ void phase_rmsnorm(const float* src, const float* __restrict__ w, u16* __restrict__ dstb, float* dstf) {
;   const int tid_ = otid();
;   const int lane = tid_ & 63;
;   const int gw = blockIdx.x * 4 + (tid_ >> 6);
;   const int nw = gridDim.x * 4;
;   float4 ww[4];
; #pragma unroll
;   for (int i = 0; i < 4; ++i) ww[i] = *(const float4*)(w + (i * 64 + lane) * 4);
;   float4 v[4], nv[4];
;   int row = gw;
;   if (row < TOK) {
; #pragma unroll
;     for (int i = 0; i < 4; ++i) v[i] = *(const float4*)(src + (size_t)row * DM + (i * 64 + lane) * 4);
;   }
;   while (row < TOK) {
;     const int nrow = row + nw;
;     if (nrow < TOK) {
; #pragma unroll
;       for (int i = 0; i < 4; ++i) nv[i] = *(const float4*)(src + (size_t)nrow * DM + (i * 64 + lane) * 4);
;     }
;     float ss = 0.f;
; #pragma unroll
;     for (int i = 0; i < 4; ++i) ss += v[i].x * v[i].x + v[i].y * v[i].y + v[i].z * v[i].z + v[i].w * v[i].w;
; #pragma unroll
;     for (int o = 1; o < 64; o <<= 1) ss += __shfl_xor(ss, o);
;     float rstd = rsqrtf(ss * (1.f / DM) + 1e-6f);
; #pragma unroll
;     for (int i = 0; i < 4; ++i) {
;       int c = (i * 64 + lane) * 4;
;       float a0 = v[i].x * rstd * ww[i].x, a1 = v[i].y * rstd * ww[i].y, a2 = v[i].z * rstd * ww[i].z, a3 = v[i].w * rstd * ww[i].w;
;       if (MODE == 0) {
;         uint2 o2; o2.x = pack2(a0, a1); o2.y = pack2(a2, a3);
;         *(uint2*)(dstb + (size_t)row * DM + c) = o2;
;       } else {
;         float4 o4; o4.x = a0; o4.y = a1; o4.z = a2; o4.w = a3;
;         *(float4*)(dstf + (size_t)row * DM + c) = o4;
;       }
;     }
.LBB0_492:
	s_or_b64 exec, exec, s[0:1]
	s_waitcnt vmcnt(0)
	v_mov_b32_e32 v30, v210
	v_readlane_b32 s0, v253, 5
	v_ashrrev_i32_e32 v0, 6, v30
	s_nop 0
	v_add_u32_e32 v50, s0, v0
	s_movk_i32 s0, 0x4000
	v_cmp_gt_i32_e32 vcc, s0, v50
	s_and_saveexec_b64 s[6:7], vcc
	s_cbranch_execz .LBB0_497
	v_readlane_b32 s56, v253, 38
	v_ashrrev_i32_e32 v51, 31, v50
	v_lshlrev_b32_e32 v0, 4, v30
	v_readlane_b32 s57, v253, 39
	v_lshlrev_b64 v[18:19], 12, v[50:51]
	v_and_b32_e32 v0, 0x3f0, v0
	v_lshl_add_u64 v[18:19], s[56:57], 0, v[18:19]
	v_readlane_b32 s58, v253, 40
	v_readlane_b32 s59, v253, 41
	v_lshl_add_u64 v[26:27], v[18:19], 0, v[0:1]
	s_nop 3
	v_readlane_b32 s38, v253, 3
	v_readlane_b32 s39, v253, 4
	s_load_dword s40, s[38:39], 0x0
	s_waitcnt lgkmcnt(0)
	s_cmpk_lg_u32 s40, 0x200
	s_cbranch_scc1 .Lrmsa_std
	global_load_dwordx4 v[2:5], v0, s[58:59]
	global_load_dwordx4 v[6:9], v0, s[58:59] offset:1024
	global_load_dwordx4 v[10:13], v0, s[58:59] offset:2048
	global_load_dwordx4 v[14:17], v0, s[58:59] offset:3072
	v_bfe_u32 v146, v50, 2, 3
	v_lshrrev_b32_e32 v147, 5, v50
	v_and_b32_e32 v148, 3, v50
	v_lshlrev_b32_e32 v146, 11, v146
	v_lshl_or_b32 v147, v147, 2, v148
	v_or_b32_e32 v146, v146, v147
	v_sub_u32_e32 v148, v146, v50
	v_mov_b32_e32 v147, 0
	v_ashrrev_i32_e32 v149, 31, v148
	v_lshlrev_b64 v[148:149], 12, v[148:149]
	v_lshl_add_u64 v[154:155], v[26:27], 0, v[148:149]
	s_mov_b32 s38, 0x100000
	s_mov_b32 s39, 0
	v_lshlrev_b64 v[156:157], 11, v[146:147]
	v_and_b32_e32 v158, 63, v210
	v_lshl_or_b32 v156, v158, 3, v156
	v_lshl_add_u64 v[156:157], s[36:37], 0, v[156:157]
	s_mov_b32 s40, 0x80000
	s_mov_b32 s41, 0
	global_load_dwordx4 v[18:21], v[154:155], off
	global_load_dwordx4 v[22:25], v[154:155], off offset:1024
	global_load_dwordx4 v[26:29], v[154:155], off offset:2048
	global_load_dwordx4 v[30:33], v[154:155], off offset:3072
	v_lshl_add_u64 v[154:155], v[154:155], 0, s[38:39]
	global_load_dwordx4 v[34:37], v[154:155], off
	global_load_dwordx4 v[38:41], v[154:155], off offset:1024
	global_load_dwordx4 v[42:45], v[154:155], off offset:2048
	global_load_dwordx4 v[46:49], v[154:155], off offset:3072
	v_lshl_add_u64 v[154:155], v[154:155], 0, s[38:39]
	global_load_dwordx4 v[50:53], v[154:155], off
	global_load_dwordx4 v[54:57], v[154:155], off offset:1024
	global_load_dwordx4 v[58:61], v[154:155], off offset:2048
	global_load_dwordx4 v[62:65], v[154:155], off offset:3072
	v_lshl_add_u64 v[154:155], v[154:155], 0, s[38:39]
	global_load_dwordx4 v[66:69], v[154:155], off
	global_load_dwordx4 v[70:73], v[154:155], off offset:1024
	global_load_dwordx4 v[74:77], v[154:155], off offset:2048
	global_load_dwordx4 v[78:81], v[154:155], off offset:3072
	v_lshl_add_u64 v[154:155], v[154:155], 0, s[38:39]
	global_load_dwordx4 v[82:85], v[154:155], off
	global_load_dwordx4 v[86:89], v[154:155], off offset:1024
	global_load_dwordx4 v[90:93], v[154:155], off offset:2048
	global_load_dwordx4 v[94:97], v[154:155], off offset:3072
	v_lshl_add_u64 v[154:155], v[154:155], 0, s[38:39]
	global_load_dwordx4 v[98:101], v[154:155], off
	global_load_dwordx4 v[102:105], v[154:155], off offset:1024
	global_load_dwordx4 v[106:109], v[154:155], off offset:2048
	global_load_dwordx4 v[110:113], v[154:155], off offset:3072
	v_lshl_add_u64 v[154:155], v[154:155], 0, s[38:39]
	global_load_dwordx4 v[114:117], v[154:155], off
	global_load_dwordx4 v[118:121], v[154:155], off offset:1024
	global_load_dwordx4 v[122:125], v[154:155], off offset:2048
	global_load_dwordx4 v[126:129], v[154:155], off offset:3072
	v_lshl_add_u64 v[154:155], v[154:155], 0, s[38:39]
	global_load_dwordx4 v[130:133], v[154:155], off
	global_load_dwordx4 v[134:137], v[154:155], off offset:1024
	global_load_dwordx4 v[138:141], v[154:155], off offset:2048
	global_load_dwordx4 v[142:145], v[154:155], off offset:3072
	s_waitcnt vmcnt(28)
	v_mul_f32_e32 v146, v22, v22
	v_mul_f32_e32 v147, v18, v18
	v_fmac_f32_e32 v146, v23, v23
	v_fmac_f32_e32 v147, v19, v19
	v_fmac_f32_e32 v146, v24, v24
	v_fmac_f32_e32 v147, v20, v20
	v_fmac_f32_e32 v146, v25, v25
	v_fmac_f32_e32 v147, v21, v21
	v_mul_f32_e32 v148, v30, v30
	v_mul_f32_e32 v149, v26, v26
	v_fmac_f32_e32 v148, v31, v31
	v_fmac_f32_e32 v149, v27, v27
	v_fmac_f32_e32 v148, v32, v32
	v_fmac_f32_e32 v149, v28, v28
	v_fmac_f32_e32 v148, v33, v33
	v_fmac_f32_e32 v149, v29, v29
	v_add_f32_e32 v150, v146, v147
	v_add_f32_e32 v150, v149, v150
	v_add_f32_e32 v150, v148, v150
	s_nop 1
	v_add_f32_dpp v150, v150, v150 quad_perm:[1,0,3,2] row_mask:0xf bank_mask:0xf
	s_nop 1
	v_add_f32_dpp v150, v150, v150 quad_perm:[2,3,0,1] row_mask:0xf bank_mask:0xf
	s_nop 1
	v_add_f32_dpp v150, v150, v150 row_half_mirror row_mask:0xf bank_mask:0xf
	s_nop 1
	v_add_f32_dpp v150, v150, v150 row_mirror row_mask:0xf bank_mask:0xf
	v_mov_b32_e32 v151, v150
	s_nop 1
	v_permlane16_swap_b32_e32 v150, v151
	s_nop 1
	v_add_f32_e32 v150, v150, v151
	v_mov_b32_e32 v151, v150
	s_nop 1
	v_permlane32_swap_b32_e32 v150, v151
	s_nop 1
	v_add_f32_e32 v150, v150, v151
	v_fmamk_f32 v150, v150, 0x3a800000, v211
	v_cmp_gt_f32_e32 vcc, 0x800000, v150
	v_mul_f32_e32 v151, 0x4b800000, v150
	s_nop 0
	v_cndmask_b32_e32 v150, v150, v151, vcc
	v_rsq_f32_e32 v150, v150
	s_nop 0
	v_mul_f32_e32 v151, 0x45800000, v150
	v_cndmask_b32_e32 v150, v150, v151, vcc
	v_mul_f32_e32 v18, v18, v150
	v_mul_f32_e32 v19, v19, v150
	v_mul_f32_e32 v20, v20, v150
	v_mul_f32_e32 v21, v21, v150
	v_mul_f32_e32 v18, v2, v18
	v_mul_f32_e32 v19, v3, v19
	v_mul_f32_e32 v20, v4, v20
	v_mul_f32_e32 v21, v5, v21
	v_cvt_pk_bf16_f32 v18, v18, v19
	v_cvt_pk_bf16_f32 v19, v20, v21
	global_store_dwordx2 v[156:157], v[18:19], off
	v_mul_f32_e32 v22, v22, v150
	v_mul_f32_e32 v23, v23, v150
	v_mul_f32_e32 v24, v24, v150
	v_mul_f32_e32 v25, v25, v150
	v_mul_f32_e32 v22, v6, v22
	v_mul_f32_e32 v23, v7, v23
	v_mul_f32_e32 v24, v8, v24
	v_mul_f32_e32 v25, v9, v25
	v_cvt_pk_bf16_f32 v22, v22, v23
	v_cvt_pk_bf16_f32 v23, v24, v25
	global_store_dwordx2 v[156:157], v[22:23], off offset:512
	v_mul_f32_e32 v26, v26, v150
	v_mul_f32_e32 v27, v27, v150
	v_mul_f32_e32 v28, v28, v150
	v_mul_f32_e32 v29, v29, v150
	v_mul_f32_e32 v26, v10, v26
	v_mul_f32_e32 v27, v11, v27
	v_mul_f32_e32 v28, v12, v28
	v_mul_f32_e32 v29, v13, v29
	v_cvt_pk_bf16_f32 v26, v26, v27
	v_cvt_pk_bf16_f32 v27, v28, v29
	global_store_dwordx2 v[156:157], v[26:27], off offset:1024
	v_mul_f32_e32 v30, v30, v150
	v_mul_f32_e32 v31, v31, v150
	v_mul_f32_e32 v32, v32, v150
	v_mul_f32_e32 v33, v33, v150
	v_mul_f32_e32 v30, v14, v30
	v_mul_f32_e32 v31, v15, v31
	v_mul_f32_e32 v32, v16, v32
	v_mul_f32_e32 v33, v17, v33
	v_cvt_pk_bf16_f32 v30, v30, v31
	v_cvt_pk_bf16_f32 v31, v32, v33
	global_store_dwordx2 v[156:157], v[30:31], off offset:1536
	v_lshl_add_u64 v[156:157], v[156:157], 0, s[40:41]
	s_waitcnt vmcnt(28)
; template <int MODE>
; __device__ void phase_rmsnorm(const float* src, const float* __restrict__ w, u16* __restrict__ dstb, float* dstf) {
;     ...
;     float ss = 0.f;
; #pragma unroll
;     for (int i = 0; i < 4; ++i) ss += v[i].x * v[i].x + v[i].y * v[i].y + v[i].z * v[i].z + v[i].w * v[i].w;
; #pragma unroll
;     for (int o = 1; o < 64; o <<= 1) ss += __shfl_xor(ss, o);
;     float rstd = rsqrtf(ss * (1.f / DM) + 1e-6f);
; #pragma unroll
;     for (int i = 0; i < 4; ++i) {
;       int c = (i * 64 + lane) * 4;
;       float a0 = v[i].x * rstd * ww[i].x, a1 = v[i].y * rstd * ww[i].y, a2 = v[i].z * rstd * ww[i].z, a3 = v[i].w * rstd * ww[i].w;
;       if (MODE == 0) {
;         uint2 o2; o2.x = pack2(a0, a1); o2.y = pack2(a2, a3);
;         *(uint2*)(dstb + (size_t)row * DM + c) = o2;
;       } else {
;         float4 o4; o4.x = a0; o4.y = a1; o4.z = a2; o4.w = a3;
;         *(float4*)(dstf + (size_t)row * DM + c) = o4;
;       }
;     }
	v_mul_f32_e32 v146, v38, v38
	v_mul_f32_e32 v147, v34, v34
	v_fmac_f32_e32 v146, v39, v39
	v_fmac_f32_e32 v147, v35, v35
	v_fmac_f32_e32 v146, v40, v40
	v_fmac_f32_e32 v147, v36, v36
	v_fmac_f32_e32 v146, v41, v41
	v_fmac_f32_e32 v147, v37, v37
	v_mul_f32_e32 v148, v46, v46
	v_mul_f32_e32 v149, v42, v42
	v_fmac_f32_e32 v148, v47, v47
	v_fmac_f32_e32 v149, v43, v43
	v_fmac_f32_e32 v148, v48, v48
	v_fmac_f32_e32 v149, v44, v44
	v_fmac_f32_e32 v148, v49, v49
	v_fmac_f32_e32 v149, v45, v45
	v_add_f32_e32 v150, v146, v147
	v_add_f32_e32 v150, v149, v150
	v_add_f32_e32 v150, v148, v150
	s_nop 1
	v_add_f32_dpp v150, v150, v150 quad_perm:[1,0,3,2] row_mask:0xf bank_mask:0xf
	s_nop 1
	v_add_f32_dpp v150, v150, v150 quad_perm:[2,3,0,1] row_mask:0xf bank_mask:0xf
	s_nop 1
	v_add_f32_dpp v150, v150, v150 row_half_mirror row_mask:0xf bank_mask:0xf
	s_nop 1
	v_add_f32_dpp v150, v150, v150 row_mirror row_mask:0xf bank_mask:0xf
	v_mov_b32_e32 v151, v150
	s_nop 1
	v_permlane16_swap_b32_e32 v150, v151
	s_nop 1
	v_add_f32_e32 v150, v150, v151
	v_mov_b32_e32 v151, v150
	s_nop 1
	v_permlane32_swap_b32_e32 v150, v151
	s_nop 1
	v_add_f32_e32 v150, v150, v151
	v_fmamk_f32 v150, v150, 0x3a800000, v211
	v_cmp_gt_f32_e32 vcc, 0x800000, v150
	v_mul_f32_e32 v151, 0x4b800000, v150
	s_nop 0
	v_cndmask_b32_e32 v150, v150, v151, vcc
	v_rsq_f32_e32 v150, v150
	s_nop 0
	v_mul_f32_e32 v151, 0x45800000, v150
	v_cndmask_b32_e32 v150, v150, v151, vcc
	v_mul_f32_e32 v34, v34, v150
	v_mul_f32_e32 v35, v35, v150
	v_mul_f32_e32 v36, v36, v150
	v_mul_f32_e32 v37, v37, v150
	v_mul_f32_e32 v34, v2, v34
	v_mul_f32_e32 v35, v3, v35
	v_mul_f32_e32 v36, v4, v36
	v_mul_f32_e32 v37, v5, v37
	v_cvt_pk_bf16_f32 v34, v34, v35
	v_cvt_pk_bf16_f32 v35, v36, v37
	global_store_dwordx2 v[156:157], v[34:35], off
	v_mul_f32_e32 v38, v38, v150
	v_mul_f32_e32 v39, v39, v150
	v_mul_f32_e32 v40, v40, v150
	v_mul_f32_e32 v41, v41, v150
	v_mul_f32_e32 v38, v6, v38
	v_mul_f32_e32 v39, v7, v39
	v_mul_f32_e32 v40, v8, v40
	v_mul_f32_e32 v41, v9, v41
	v_cvt_pk_bf16_f32 v38, v38, v39
	v_cvt_pk_bf16_f32 v39, v40, v41
	global_store_dwordx2 v[156:157], v[38:39], off offset:512
	v_mul_f32_e32 v42, v42, v150
	v_mul_f32_e32 v43, v43, v150
	v_mul_f32_e32 v44, v44, v150
	v_mul_f32_e32 v45, v45, v150
	v_mul_f32_e32 v42, v10, v42
	v_mul_f32_e32 v43, v11, v43
	v_mul_f32_e32 v44, v12, v44
	v_mul_f32_e32 v45, v13, v45
	v_cvt_pk_bf16_f32 v42, v42, v43
	v_cvt_pk_bf16_f32 v43, v44, v45
	global_store_dwordx2 v[156:157], v[42:43], off offset:1024
	v_mul_f32_e32 v46, v46, v150
	v_mul_f32_e32 v47, v47, v150
	v_mul_f32_e32 v48, v48, v150
	v_mul_f32_e32 v49, v49, v150
	v_mul_f32_e32 v46, v14, v46
	v_mul_f32_e32 v47, v15, v47
	v_mul_f32_e32 v48, v16, v48
	v_mul_f32_e32 v49, v17, v49
	v_cvt_pk_bf16_f32 v46, v46, v47
	v_cvt_pk_bf16_f32 v47, v48, v49
	global_store_dwordx2 v[156:157], v[46:47], off offset:1536
	v_lshl_add_u64 v[156:157], v[156:157], 0, s[40:41]
	s_waitcnt vmcnt(28)
	v_mul_f32_e32 v146, v54, v54
	v_mul_f32_e32 v147, v50, v50
	v_fmac_f32_e32 v146, v55, v55
	v_fmac_f32_e32 v147, v51, v51
	v_fmac_f32_e32 v146, v56, v56
	v_fmac_f32_e32 v147, v52, v52
	v_fmac_f32_e32 v146, v57, v57
	v_fmac_f32_e32 v147, v53, v53
	v_mul_f32_e32 v148, v62, v62
	v_mul_f32_e32 v149, v58, v58
	v_fmac_f32_e32 v148, v63, v63
	v_fmac_f32_e32 v149, v59, v59
	v_fmac_f32_e32 v148, v64, v64
	v_fmac_f32_e32 v149, v60, v60
	v_fmac_f32_e32 v148, v65, v65
	v_fmac_f32_e32 v149, v61, v61
	v_add_f32_e32 v150, v146, v147
	v_add_f32_e32 v150, v149, v150
	v_add_f32_e32 v150, v148, v150
	s_nop 1
	v_add_f32_dpp v150, v150, v150 quad_perm:[1,0,3,2] row_mask:0xf bank_mask:0xf
	s_nop 1
	v_add_f32_dpp v150, v150, v150 quad_perm:[2,3,0,1] row_mask:0xf bank_mask:0xf
	s_nop 1
	v_add_f32_dpp v150, v150, v150 row_half_mirror row_mask:0xf bank_mask:0xf
	s_nop 1
	v_add_f32_dpp v150, v150, v150 row_mirror row_mask:0xf bank_mask:0xf
	v_mov_b32_e32 v151, v150
	s_nop 1
	v_permlane16_swap_b32_e32 v150, v151
	s_nop 1
	v_add_f32_e32 v150, v150, v151
	v_mov_b32_e32 v151, v150
	s_nop 1
	v_permlane32_swap_b32_e32 v150, v151
	s_nop 1
	v_add_f32_e32 v150, v150, v151
	v_fmamk_f32 v150, v150, 0x3a800000, v211
	v_cmp_gt_f32_e32 vcc, 0x800000, v150
	v_mul_f32_e32 v151, 0x4b800000, v150
	s_nop 0
	v_cndmask_b32_e32 v150, v150, v151, vcc
	v_rsq_f32_e32 v150, v150
	s_nop 0
	v_mul_f32_e32 v151, 0x45800000, v150
	v_cndmask_b32_e32 v150, v150, v151, vcc
	v_mul_f32_e32 v50, v50, v150
	v_mul_f32_e32 v51, v51, v150
	v_mul_f32_e32 v52, v52, v150
	v_mul_f32_e32 v53, v53, v150
	v_mul_f32_e32 v50, v2, v50
	v_mul_f32_e32 v51, v3, v51
	v_mul_f32_e32 v52, v4, v52
	v_mul_f32_e32 v53, v5, v53
	v_cvt_pk_bf16_f32 v50, v50, v51
	v_cvt_pk_bf16_f32 v51, v52, v53
	global_store_dwordx2 v[156:157], v[50:51], off
	v_mul_f32_e32 v54, v54, v150
	v_mul_f32_e32 v55, v55, v150
	v_mul_f32_e32 v56, v56, v150
	v_mul_f32_e32 v57, v57, v150
	v_mul_f32_e32 v54, v6, v54
	v_mul_f32_e32 v55, v7, v55
	v_mul_f32_e32 v56, v8, v56
	v_mul_f32_e32 v57, v9, v57
	v_cvt_pk_bf16_f32 v54, v54, v55
	v_cvt_pk_bf16_f32 v55, v56, v57
	global_store_dwordx2 v[156:157], v[54:55], off offset:512
	v_mul_f32_e32 v58, v58, v150
	v_mul_f32_e32 v59, v59, v150
	v_mul_f32_e32 v60, v60, v150
	v_mul_f32_e32 v61, v61, v150
	v_mul_f32_e32 v58, v10, v58
	v_mul_f32_e32 v59, v11, v59
	v_mul_f32_e32 v60, v12, v60
	v_mul_f32_e32 v61, v13, v61
	v_cvt_pk_bf16_f32 v58, v58, v59
	v_cvt_pk_bf16_f32 v59, v60, v61
	global_store_dwordx2 v[156:157], v[58:59], off offset:1024
	v_mul_f32_e32 v62, v62, v150
	v_mul_f32_e32 v63, v63, v150
	v_mul_f32_e32 v64, v64, v150
	v_mul_f32_e32 v65, v65, v150
	v_mul_f32_e32 v62, v14, v62
	v_mul_f32_e32 v63, v15, v63
	v_mul_f32_e32 v64, v16, v64
	v_mul_f32_e32 v65, v17, v65
	v_cvt_pk_bf16_f32 v62, v62, v63
	v_cvt_pk_bf16_f32 v63, v64, v65
	global_store_dwordx2 v[156:157], v[62:63], off offset:1536
	v_lshl_add_u64 v[156:157], v[156:157], 0, s[40:41]
	s_waitcnt vmcnt(28)
; template <int MODE>
; __device__ void phase_rmsnorm(const float* src, const float* __restrict__ w, u16* __restrict__ dstb, float* dstf) {
;     ...
;     float ss = 0.f;
; #pragma unroll
;     for (int i = 0; i < 4; ++i) ss += v[i].x * v[i].x + v[i].y * v[i].y + v[i].z * v[i].z + v[i].w * v[i].w;
; #pragma unroll
;     for (int o = 1; o < 64; o <<= 1) ss += __shfl_xor(ss, o);
;     float rstd = rsqrtf(ss * (1.f / DM) + 1e-6f);
; #pragma unroll
;     for (int i = 0; i < 4; ++i) {
;       int c = (i * 64 + lane) * 4;
;       float a0 = v[i].x * rstd * ww[i].x, a1 = v[i].y * rstd * ww[i].y, a2 = v[i].z * rstd * ww[i].z, a3 = v[i].w * rstd * ww[i].w;
;       if (MODE == 0) {
;         uint2 o2; o2.x = pack2(a0, a1); o2.y = pack2(a2, a3);
;         *(uint2*)(dstb + (size_t)row * DM + c) = o2;
;       } else {
;         float4 o4; o4.x = a0; o4.y = a1; o4.z = a2; o4.w = a3;
;         *(float4*)(dstf + (size_t)row * DM + c) = o4;
;       }
;     }
	v_mul_f32_e32 v146, v70, v70
	v_mul_f32_e32 v147, v66, v66
	v_fmac_f32_e32 v146, v71, v71
	v_fmac_f32_e32 v147, v67, v67
	v_fmac_f32_e32 v146, v72, v72
	v_fmac_f32_e32 v147, v68, v68
	v_fmac_f32_e32 v146, v73, v73
	v_fmac_f32_e32 v147, v69, v69
	v_mul_f32_e32 v148, v78, v78
	v_mul_f32_e32 v149, v74, v74
	v_fmac_f32_e32 v148, v79, v79
	v_fmac_f32_e32 v149, v75, v75
	v_fmac_f32_e32 v148, v80, v80
	v_fmac_f32_e32 v149, v76, v76
	v_fmac_f32_e32 v148, v81, v81
	v_fmac_f32_e32 v149, v77, v77
	v_add_f32_e32 v150, v146, v147
	v_add_f32_e32 v150, v149, v150
	v_add_f32_e32 v150, v148, v150
	s_nop 1
	v_add_f32_dpp v150, v150, v150 quad_perm:[1,0,3,2] row_mask:0xf bank_mask:0xf
	s_nop 1
	v_add_f32_dpp v150, v150, v150 quad_perm:[2,3,0,1] row_mask:0xf bank_mask:0xf
	s_nop 1
	v_add_f32_dpp v150, v150, v150 row_half_mirror row_mask:0xf bank_mask:0xf
	s_nop 1
	v_add_f32_dpp v150, v150, v150 row_mirror row_mask:0xf bank_mask:0xf
	v_mov_b32_e32 v151, v150
	s_nop 1
	v_permlane16_swap_b32_e32 v150, v151
	s_nop 1
	v_add_f32_e32 v150, v150, v151
	v_mov_b32_e32 v151, v150
	s_nop 1
	v_permlane32_swap_b32_e32 v150, v151
	s_nop 1
	v_add_f32_e32 v150, v150, v151
	v_fmamk_f32 v150, v150, 0x3a800000, v211
	v_cmp_gt_f32_e32 vcc, 0x800000, v150
	v_mul_f32_e32 v151, 0x4b800000, v150
	s_nop 0
	v_cndmask_b32_e32 v150, v150, v151, vcc
	v_rsq_f32_e32 v150, v150
	s_nop 0
	v_mul_f32_e32 v151, 0x45800000, v150
	v_cndmask_b32_e32 v150, v150, v151, vcc
	v_mul_f32_e32 v66, v66, v150
	v_mul_f32_e32 v67, v67, v150
	v_mul_f32_e32 v68, v68, v150
	v_mul_f32_e32 v69, v69, v150
	v_mul_f32_e32 v66, v2, v66
	v_mul_f32_e32 v67, v3, v67
	v_mul_f32_e32 v68, v4, v68
	v_mul_f32_e32 v69, v5, v69
	v_cvt_pk_bf16_f32 v66, v66, v67
	v_cvt_pk_bf16_f32 v67, v68, v69
	global_store_dwordx2 v[156:157], v[66:67], off
	v_mul_f32_e32 v70, v70, v150
	v_mul_f32_e32 v71, v71, v150
	v_mul_f32_e32 v72, v72, v150
	v_mul_f32_e32 v73, v73, v150
	v_mul_f32_e32 v70, v6, v70
	v_mul_f32_e32 v71, v7, v71
	v_mul_f32_e32 v72, v8, v72
	v_mul_f32_e32 v73, v9, v73
	v_cvt_pk_bf16_f32 v70, v70, v71
	v_cvt_pk_bf16_f32 v71, v72, v73
	global_store_dwordx2 v[156:157], v[70:71], off offset:512
	v_mul_f32_e32 v74, v74, v150
	v_mul_f32_e32 v75, v75, v150
	v_mul_f32_e32 v76, v76, v150
	v_mul_f32_e32 v77, v77, v150
	v_mul_f32_e32 v74, v10, v74
	v_mul_f32_e32 v75, v11, v75
	v_mul_f32_e32 v76, v12, v76
	v_mul_f32_e32 v77, v13, v77
	v_cvt_pk_bf16_f32 v74, v74, v75
	v_cvt_pk_bf16_f32 v75, v76, v77
	global_store_dwordx2 v[156:157], v[74:75], off offset:1024
	v_mul_f32_e32 v78, v78, v150
	v_mul_f32_e32 v79, v79, v150
	v_mul_f32_e32 v80, v80, v150
	v_mul_f32_e32 v81, v81, v150
	v_mul_f32_e32 v78, v14, v78
	v_mul_f32_e32 v79, v15, v79
	v_mul_f32_e32 v80, v16, v80
	v_mul_f32_e32 v81, v17, v81
	v_cvt_pk_bf16_f32 v78, v78, v79
	v_cvt_pk_bf16_f32 v79, v80, v81
	global_store_dwordx2 v[156:157], v[78:79], off offset:1536
	v_lshl_add_u64 v[156:157], v[156:157], 0, s[40:41]
	s_waitcnt vmcnt(28)
	v_mul_f32_e32 v146, v86, v86
	v_mul_f32_e32 v147, v82, v82
	v_fmac_f32_e32 v146, v87, v87
	v_fmac_f32_e32 v147, v83, v83
	v_fmac_f32_e32 v146, v88, v88
	v_fmac_f32_e32 v147, v84, v84
	v_fmac_f32_e32 v146, v89, v89
	v_fmac_f32_e32 v147, v85, v85
	v_mul_f32_e32 v148, v94, v94
	v_mul_f32_e32 v149, v90, v90
	v_fmac_f32_e32 v148, v95, v95
	v_fmac_f32_e32 v149, v91, v91
	v_fmac_f32_e32 v148, v96, v96
	v_fmac_f32_e32 v149, v92, v92
	v_fmac_f32_e32 v148, v97, v97
	v_fmac_f32_e32 v149, v93, v93
	v_add_f32_e32 v150, v146, v147
	v_add_f32_e32 v150, v149, v150
	v_add_f32_e32 v150, v148, v150
	s_nop 1
	v_add_f32_dpp v150, v150, v150 quad_perm:[1,0,3,2] row_mask:0xf bank_mask:0xf
	s_nop 1
	v_add_f32_dpp v150, v150, v150 quad_perm:[2,3,0,1] row_mask:0xf bank_mask:0xf
	s_nop 1
	v_add_f32_dpp v150, v150, v150 row_half_mirror row_mask:0xf bank_mask:0xf
	s_nop 1
	v_add_f32_dpp v150, v150, v150 row_mirror row_mask:0xf bank_mask:0xf
	v_mov_b32_e32 v151, v150
	s_nop 1
	v_permlane16_swap_b32_e32 v150, v151
	s_nop 1
	v_add_f32_e32 v150, v150, v151
	v_mov_b32_e32 v151, v150
	s_nop 1
	v_permlane32_swap_b32_e32 v150, v151
	s_nop 1
	v_add_f32_e32 v150, v150, v151
	v_fmamk_f32 v150, v150, 0x3a800000, v211
	v_cmp_gt_f32_e32 vcc, 0x800000, v150
	v_mul_f32_e32 v151, 0x4b800000, v150
	s_nop 0
	v_cndmask_b32_e32 v150, v150, v151, vcc
	v_rsq_f32_e32 v150, v150
	s_nop 0
	v_mul_f32_e32 v151, 0x45800000, v150
	v_cndmask_b32_e32 v150, v150, v151, vcc
	v_mul_f32_e32 v82, v82, v150
	v_mul_f32_e32 v83, v83, v150
	v_mul_f32_e32 v84, v84, v150
	v_mul_f32_e32 v85, v85, v150
	v_mul_f32_e32 v82, v2, v82
	v_mul_f32_e32 v83, v3, v83
	v_mul_f32_e32 v84, v4, v84
	v_mul_f32_e32 v85, v5, v85
	v_cvt_pk_bf16_f32 v82, v82, v83
	v_cvt_pk_bf16_f32 v83, v84, v85
	global_store_dwordx2 v[156:157], v[82:83], off
	v_mul_f32_e32 v86, v86, v150
	v_mul_f32_e32 v87, v87, v150
	v_mul_f32_e32 v88, v88, v150
	v_mul_f32_e32 v89, v89, v150
	v_mul_f32_e32 v86, v6, v86
	v_mul_f32_e32 v87, v7, v87
	v_mul_f32_e32 v88, v8, v88
	v_mul_f32_e32 v89, v9, v89
	v_cvt_pk_bf16_f32 v86, v86, v87
	v_cvt_pk_bf16_f32 v87, v88, v89
	global_store_dwordx2 v[156:157], v[86:87], off offset:512
	v_mul_f32_e32 v90, v90, v150
	v_mul_f32_e32 v91, v91, v150
	v_mul_f32_e32 v92, v92, v150
	v_mul_f32_e32 v93, v93, v150
	v_mul_f32_e32 v90, v10, v90
	v_mul_f32_e32 v91, v11, v91
	v_mul_f32_e32 v92, v12, v92
	v_mul_f32_e32 v93, v13, v93
	v_cvt_pk_bf16_f32 v90, v90, v91
	v_cvt_pk_bf16_f32 v91, v92, v93
	global_store_dwordx2 v[156:157], v[90:91], off offset:1024
	v_mul_f32_e32 v94, v94, v150
	v_mul_f32_e32 v95, v95, v150
	v_mul_f32_e32 v96, v96, v150
	v_mul_f32_e32 v97, v97, v150
	v_mul_f32_e32 v94, v14, v94
	v_mul_f32_e32 v95, v15, v95
	v_mul_f32_e32 v96, v16, v96
	v_mul_f32_e32 v97, v17, v97
	v_cvt_pk_bf16_f32 v94, v94, v95
	v_cvt_pk_bf16_f32 v95, v96, v97
	global_store_dwordx2 v[156:157], v[94:95], off offset:1536
	v_lshl_add_u64 v[156:157], v[156:157], 0, s[40:41]
	s_waitcnt vmcnt(28)
; template <int MODE>
; __device__ void phase_rmsnorm(const float* src, const float* __restrict__ w, u16* __restrict__ dstb, float* dstf) {
;     ...
;     float ss = 0.f;
; #pragma unroll
;     for (int i = 0; i < 4; ++i) ss += v[i].x * v[i].x + v[i].y * v[i].y + v[i].z * v[i].z + v[i].w * v[i].w;
; #pragma unroll
;     for (int o = 1; o < 64; o <<= 1) ss += __shfl_xor(ss, o);
;     float rstd = rsqrtf(ss * (1.f / DM) + 1e-6f);
; #pragma unroll
;     for (int i = 0; i < 4; ++i) {
;       int c = (i * 64 + lane) * 4;
;       float a0 = v[i].x * rstd * ww[i].x, a1 = v[i].y * rstd * ww[i].y, a2 = v[i].z * rstd * ww[i].z, a3 = v[i].w * rstd * ww[i].w;
;       if (MODE == 0) {
;         uint2 o2; o2.x = pack2(a0, a1); o2.y = pack2(a2, a3);
;         *(uint2*)(dstb + (size_t)row * DM + c) = o2;
;       } else {
;         float4 o4; o4.x = a0; o4.y = a1; o4.z = a2; o4.w = a3;
;         *(float4*)(dstf + (size_t)row * DM + c) = o4;
;       }
;     }
	v_mul_f32_e32 v146, v102, v102
	v_mul_f32_e32 v147, v98, v98
	v_fmac_f32_e32 v146, v103, v103
	v_fmac_f32_e32 v147, v99, v99
	v_fmac_f32_e32 v146, v104, v104
	v_fmac_f32_e32 v147, v100, v100
	v_fmac_f32_e32 v146, v105, v105
	v_fmac_f32_e32 v147, v101, v101
	v_mul_f32_e32 v148, v110, v110
	v_mul_f32_e32 v149, v106, v106
	v_fmac_f32_e32 v148, v111, v111
	v_fmac_f32_e32 v149, v107, v107
	v_fmac_f32_e32 v148, v112, v112
	v_fmac_f32_e32 v149, v108, v108
	v_fmac_f32_e32 v148, v113, v113
	v_fmac_f32_e32 v149, v109, v109
	v_add_f32_e32 v150, v146, v147
	v_add_f32_e32 v150, v149, v150
	v_add_f32_e32 v150, v148, v150
	s_nop 1
	v_add_f32_dpp v150, v150, v150 quad_perm:[1,0,3,2] row_mask:0xf bank_mask:0xf
	s_nop 1
	v_add_f32_dpp v150, v150, v150 quad_perm:[2,3,0,1] row_mask:0xf bank_mask:0xf
	s_nop 1
	v_add_f32_dpp v150, v150, v150 row_half_mirror row_mask:0xf bank_mask:0xf
	s_nop 1
	v_add_f32_dpp v150, v150, v150 row_mirror row_mask:0xf bank_mask:0xf
	v_mov_b32_e32 v151, v150
	s_nop 1
	v_permlane16_swap_b32_e32 v150, v151
	s_nop 1
	v_add_f32_e32 v150, v150, v151
	v_mov_b32_e32 v151, v150
	s_nop 1
	v_permlane32_swap_b32_e32 v150, v151
	s_nop 1
	v_add_f32_e32 v150, v150, v151
	v_fmamk_f32 v150, v150, 0x3a800000, v211
	v_cmp_gt_f32_e32 vcc, 0x800000, v150
	v_mul_f32_e32 v151, 0x4b800000, v150
	s_nop 0
	v_cndmask_b32_e32 v150, v150, v151, vcc
	v_rsq_f32_e32 v150, v150
	s_nop 0
	v_mul_f32_e32 v151, 0x45800000, v150
	v_cndmask_b32_e32 v150, v150, v151, vcc
	v_mul_f32_e32 v98, v98, v150
	v_mul_f32_e32 v99, v99, v150
	v_mul_f32_e32 v100, v100, v150
	v_mul_f32_e32 v101, v101, v150
	v_mul_f32_e32 v98, v2, v98
	v_mul_f32_e32 v99, v3, v99
	v_mul_f32_e32 v100, v4, v100
	v_mul_f32_e32 v101, v5, v101
	v_cvt_pk_bf16_f32 v98, v98, v99
	v_cvt_pk_bf16_f32 v99, v100, v101
	global_store_dwordx2 v[156:157], v[98:99], off
	v_mul_f32_e32 v102, v102, v150
	v_mul_f32_e32 v103, v103, v150
	v_mul_f32_e32 v104, v104, v150
	v_mul_f32_e32 v105, v105, v150
	v_mul_f32_e32 v102, v6, v102
	v_mul_f32_e32 v103, v7, v103
	v_mul_f32_e32 v104, v8, v104
	v_mul_f32_e32 v105, v9, v105
	v_cvt_pk_bf16_f32 v102, v102, v103
	v_cvt_pk_bf16_f32 v103, v104, v105
	global_store_dwordx2 v[156:157], v[102:103], off offset:512
	v_mul_f32_e32 v106, v106, v150
	v_mul_f32_e32 v107, v107, v150
	v_mul_f32_e32 v108, v108, v150
	v_mul_f32_e32 v109, v109, v150
	v_mul_f32_e32 v106, v10, v106
	v_mul_f32_e32 v107, v11, v107
	v_mul_f32_e32 v108, v12, v108
	v_mul_f32_e32 v109, v13, v109
	v_cvt_pk_bf16_f32 v106, v106, v107
	v_cvt_pk_bf16_f32 v107, v108, v109
	global_store_dwordx2 v[156:157], v[106:107], off offset:1024
	v_mul_f32_e32 v110, v110, v150
	v_mul_f32_e32 v111, v111, v150
	v_mul_f32_e32 v112, v112, v150
	v_mul_f32_e32 v113, v113, v150
	v_mul_f32_e32 v110, v14, v110
	v_mul_f32_e32 v111, v15, v111
	v_mul_f32_e32 v112, v16, v112
	v_mul_f32_e32 v113, v17, v113
	v_cvt_pk_bf16_f32 v110, v110, v111
	v_cvt_pk_bf16_f32 v111, v112, v113
	global_store_dwordx2 v[156:157], v[110:111], off offset:1536
	v_lshl_add_u64 v[156:157], v[156:157], 0, s[40:41]
	s_waitcnt vmcnt(28)
	v_mul_f32_e32 v146, v118, v118
	v_mul_f32_e32 v147, v114, v114
	v_fmac_f32_e32 v146, v119, v119
	v_fmac_f32_e32 v147, v115, v115
	v_fmac_f32_e32 v146, v120, v120
	v_fmac_f32_e32 v147, v116, v116
	v_fmac_f32_e32 v146, v121, v121
	v_fmac_f32_e32 v147, v117, v117
	v_mul_f32_e32 v148, v126, v126
	v_mul_f32_e32 v149, v122, v122
	v_fmac_f32_e32 v148, v127, v127
	v_fmac_f32_e32 v149, v123, v123
	v_fmac_f32_e32 v148, v128, v128
	v_fmac_f32_e32 v149, v124, v124
	v_fmac_f32_e32 v148, v129, v129
	v_fmac_f32_e32 v149, v125, v125
	v_add_f32_e32 v150, v146, v147
	v_add_f32_e32 v150, v149, v150
	v_add_f32_e32 v150, v148, v150
	s_nop 1
	v_add_f32_dpp v150, v150, v150 quad_perm:[1,0,3,2] row_mask:0xf bank_mask:0xf
	s_nop 1
	v_add_f32_dpp v150, v150, v150 quad_perm:[2,3,0,1] row_mask:0xf bank_mask:0xf
	s_nop 1
	v_add_f32_dpp v150, v150, v150 row_half_mirror row_mask:0xf bank_mask:0xf
	s_nop 1
	v_add_f32_dpp v150, v150, v150 row_mirror row_mask:0xf bank_mask:0xf
	v_mov_b32_e32 v151, v150
	s_nop 1
	v_permlane16_swap_b32_e32 v150, v151
	s_nop 1
	v_add_f32_e32 v150, v150, v151
	v_mov_b32_e32 v151, v150
	s_nop 1
	v_permlane32_swap_b32_e32 v150, v151
	s_nop 1
	v_add_f32_e32 v150, v150, v151
	v_fmamk_f32 v150, v150, 0x3a800000, v211
	v_cmp_gt_f32_e32 vcc, 0x800000, v150
	v_mul_f32_e32 v151, 0x4b800000, v150
	s_nop 0
	v_cndmask_b32_e32 v150, v150, v151, vcc
	v_rsq_f32_e32 v150, v150
	s_nop 0
	v_mul_f32_e32 v151, 0x45800000, v150
	v_cndmask_b32_e32 v150, v150, v151, vcc
	v_mul_f32_e32 v114, v114, v150
	v_mul_f32_e32 v115, v115, v150
	v_mul_f32_e32 v116, v116, v150
	v_mul_f32_e32 v117, v117, v150
	v_mul_f32_e32 v114, v2, v114
	v_mul_f32_e32 v115, v3, v115
	v_mul_f32_e32 v116, v4, v116
	v_mul_f32_e32 v117, v5, v117
	v_cvt_pk_bf16_f32 v114, v114, v115
	v_cvt_pk_bf16_f32 v115, v116, v117
	global_store_dwordx2 v[156:157], v[114:115], off
	v_mul_f32_e32 v118, v118, v150
	v_mul_f32_e32 v119, v119, v150
	v_mul_f32_e32 v120, v120, v150
	v_mul_f32_e32 v121, v121, v150
	v_mul_f32_e32 v118, v6, v118
	v_mul_f32_e32 v119, v7, v119
	v_mul_f32_e32 v120, v8, v120
	v_mul_f32_e32 v121, v9, v121
	v_cvt_pk_bf16_f32 v118, v118, v119
	v_cvt_pk_bf16_f32 v119, v120, v121
	global_store_dwordx2 v[156:157], v[118:119], off offset:512
	v_mul_f32_e32 v122, v122, v150
	v_mul_f32_e32 v123, v123, v150
	v_mul_f32_e32 v124, v124, v150
	v_mul_f32_e32 v125, v125, v150
	v_mul_f32_e32 v122, v10, v122
	v_mul_f32_e32 v123, v11, v123
	v_mul_f32_e32 v124, v12, v124
	v_mul_f32_e32 v125, v13, v125
	v_cvt_pk_bf16_f32 v122, v122, v123
	v_cvt_pk_bf16_f32 v123, v124, v125
	global_store_dwordx2 v[156:157], v[122:123], off offset:1024
	v_mul_f32_e32 v126, v126, v150
	v_mul_f32_e32 v127, v127, v150
	v_mul_f32_e32 v128, v128, v150
	v_mul_f32_e32 v129, v129, v150
	v_mul_f32_e32 v126, v14, v126
	v_mul_f32_e32 v127, v15, v127
	v_mul_f32_e32 v128, v16, v128
	v_mul_f32_e32 v129, v17, v129
	v_cvt_pk_bf16_f32 v126, v126, v127
	v_cvt_pk_bf16_f32 v127, v128, v129
	global_store_dwordx2 v[156:157], v[126:127], off offset:1536
	v_lshl_add_u64 v[156:157], v[156:157], 0, s[40:41]
	s_waitcnt vmcnt(28)
; __device__ __forceinline__ int otid() { int t = threadIdx.x; asm volatile("" : "+v"(t)); return t; }
; template <int MODE>
; __device__ void phase_rmsnorm(const float* src, const float* __restrict__ w, u16* __restrict__ dstb, float* dstf) {
;   const int tid_ = otid();
;   const int lane = tid_ & 63;
;   const int gw = blockIdx.x * 4 + (tid_ >> 6);
;   const int nw = gridDim.x * 4;
;   float4 ww[4];
; #pragma unroll
;   for (int i = 0; i < 4; ++i) ww[i] = *(const float4*)(w + (i * 64 + lane) * 4);
;   float4 v[4], nv[4];
;   int row = gw;
;   if (row < TOK) {
; #pragma unroll
;     for (int i = 0; i < 4; ++i) v[i] = *(const float4*)(src + (size_t)row * DM + (i * 64 + lane) * 4);
;   }
;   while (row < TOK) {
;     const int nrow = row + nw;
;     if (nrow < TOK) {
; #pragma unroll
;       for (int i = 0; i < 4; ++i) nv[i] = *(const float4*)(src + (size_t)nrow * DM + (i * 64 + lane) * 4);
;     }
;     float ss = 0.f;
; #pragma unroll
;     for (int i = 0; i < 4; ++i) ss += v[i].x * v[i].x + v[i].y * v[i].y + v[i].z * v[i].z + v[i].w * v[i].w;
; #pragma unroll
;     for (int o = 1; o < 64; o <<= 1) ss += __shfl_xor(ss, o);
;     float rstd = rsqrtf(ss * (1.f / DM) + 1e-6f);
; #pragma unroll
;     for (int i = 0; i < 4; ++i) {
;       int c = (i * 64 + lane) * 4;
;       float a0 = v[i].x * rstd * ww[i].x, a1 = v[i].y * rstd * ww[i].y, a2 = v[i].z * rstd * ww[i].z, a3 = v[i].w * rstd * ww[i].w;
;       if (MODE == 0) {
;         uint2 o2; o2.x = pack2(a0, a1); o2.y = pack2(a2, a3);
;         *(uint2*)(dstb + (size_t)row * DM + c) = o2;
;       } else {
;         float4 o4; o4.x = a0; o4.y = a1; o4.z = a2; o4.w = a3;
;         *(float4*)(dstf + (size_t)row * DM + c) = o4;
;       }
;     }
	v_mul_f32_e32 v146, v134, v134
	v_mul_f32_e32 v147, v130, v130
	v_fmac_f32_e32 v146, v135, v135
	v_fmac_f32_e32 v147, v131, v131
	v_fmac_f32_e32 v146, v136, v136
	v_fmac_f32_e32 v147, v132, v132
	v_fmac_f32_e32 v146, v137, v137
	v_fmac_f32_e32 v147, v133, v133
	v_mul_f32_e32 v148, v142, v142
	v_mul_f32_e32 v149, v138, v138
	v_fmac_f32_e32 v148, v143, v143
	v_fmac_f32_e32 v149, v139, v139
	v_fmac_f32_e32 v148, v144, v144
	v_fmac_f32_e32 v149, v140, v140
	v_fmac_f32_e32 v148, v145, v145
	v_fmac_f32_e32 v149, v141, v141
	v_add_f32_e32 v150, v146, v147
	v_add_f32_e32 v150, v149, v150
	v_add_f32_e32 v150, v148, v150
	s_nop 1
	v_add_f32_dpp v150, v150, v150 quad_perm:[1,0,3,2] row_mask:0xf bank_mask:0xf
	s_nop 1
	v_add_f32_dpp v150, v150, v150 quad_perm:[2,3,0,1] row_mask:0xf bank_mask:0xf
	s_nop 1
	v_add_f32_dpp v150, v150, v150 row_half_mirror row_mask:0xf bank_mask:0xf
	s_nop 1
	v_add_f32_dpp v150, v150, v150 row_mirror row_mask:0xf bank_mask:0xf
	v_mov_b32_e32 v151, v150
	s_nop 1
	v_permlane16_swap_b32_e32 v150, v151
	s_nop 1
	v_add_f32_e32 v150, v150, v151
	v_mov_b32_e32 v151, v150
	s_nop 1
	v_permlane32_swap_b32_e32 v150, v151
	s_nop 1
	v_add_f32_e32 v150, v150, v151
	v_fmamk_f32 v150, v150, 0x3a800000, v211
	v_cmp_gt_f32_e32 vcc, 0x800000, v150
	v_mul_f32_e32 v151, 0x4b800000, v150
	s_nop 0
	v_cndmask_b32_e32 v150, v150, v151, vcc
	v_rsq_f32_e32 v150, v150
	s_nop 0
	v_mul_f32_e32 v151, 0x45800000, v150
	v_cndmask_b32_e32 v150, v150, v151, vcc
	v_mul_f32_e32 v130, v130, v150
	v_mul_f32_e32 v131, v131, v150
	v_mul_f32_e32 v132, v132, v150
	v_mul_f32_e32 v133, v133, v150
	v_mul_f32_e32 v130, v2, v130
	v_mul_f32_e32 v131, v3, v131
	v_mul_f32_e32 v132, v4, v132
	v_mul_f32_e32 v133, v5, v133
	v_cvt_pk_bf16_f32 v130, v130, v131
	v_cvt_pk_bf16_f32 v131, v132, v133
	global_store_dwordx2 v[156:157], v[130:131], off
	v_mul_f32_e32 v134, v134, v150
	v_mul_f32_e32 v135, v135, v150
	v_mul_f32_e32 v136, v136, v150
	v_mul_f32_e32 v137, v137, v150
	v_mul_f32_e32 v134, v6, v134
	v_mul_f32_e32 v135, v7, v135
	v_mul_f32_e32 v136, v8, v136
	v_mul_f32_e32 v137, v9, v137
	v_cvt_pk_bf16_f32 v134, v134, v135
	v_cvt_pk_bf16_f32 v135, v136, v137
	global_store_dwordx2 v[156:157], v[134:135], off offset:512
	v_mul_f32_e32 v138, v138, v150
	v_mul_f32_e32 v139, v139, v150
	v_mul_f32_e32 v140, v140, v150
	v_mul_f32_e32 v141, v141, v150
	v_mul_f32_e32 v138, v10, v138
	v_mul_f32_e32 v139, v11, v139
	v_mul_f32_e32 v140, v12, v140
	v_mul_f32_e32 v141, v13, v141
	v_cvt_pk_bf16_f32 v138, v138, v139
	v_cvt_pk_bf16_f32 v139, v140, v141
	global_store_dwordx2 v[156:157], v[138:139], off offset:1024
	v_mul_f32_e32 v142, v142, v150
	v_mul_f32_e32 v143, v143, v150
	v_mul_f32_e32 v144, v144, v150
	v_mul_f32_e32 v145, v145, v150
	v_mul_f32_e32 v142, v14, v142
	v_mul_f32_e32 v143, v15, v143
	v_mul_f32_e32 v144, v16, v144
	v_mul_f32_e32 v145, v17, v145
	v_cvt_pk_bf16_f32 v142, v142, v143
	v_cvt_pk_bf16_f32 v143, v144, v145
	global_store_dwordx2 v[156:157], v[142:143], off offset:1536
	s_branch .LBB0_497
.Lrmsa_std:
	global_load_dwordx4 v[2:5], v0, s[58:59]
	global_load_dwordx4 v[6:9], v0, s[58:59] offset:1024
	global_load_dwordx4 v[10:13], v0, s[58:59] offset:2048
	global_load_dwordx4 v[14:17], v0, s[58:59] offset:3072
	global_load_dwordx4 v[34:37], v[26:27], off
	global_load_dwordx4 v[18:21], v[26:27], off offset:1024
	global_load_dwordx4 v[22:25], v[26:27], off offset:2048
	s_nop 0
	global_load_dwordx4 v[26:29], v[26:27], off offset:3072
	v_cmp_lt_i32_e32 vcc, v250, v217
	s_lshl_b32 s8, s12, 2
	v_and_b32_e32 v38, 63, v30
	v_cndmask_b32_e32 v0, v215, v250, vcc
	v_cmp_lt_i32_e32 vcc, v251, v217
	v_add_u32_e32 v30, s8, v50
	v_lshlrev_b64 v[32:33], 11, v[50:51]
	v_cndmask_b32_e32 v31, v215, v251, vcc
	v_cmp_lt_i32_e32 vcc, v252, v217
	v_lshlrev_b32_e32 v56, 2, v31
	v_lshl_or_b32 v32, v38, 3, v32
	v_cndmask_b32_e32 v31, v215, v252, vcc
	v_lshlrev_b32_e32 v57, 2, v31
	v_xor_b32_e32 v31, 8, v215
	v_cmp_lt_i32_e32 vcc, v31, v217
	s_ashr_i32 s9, s8, 31
	v_lshlrev_b32_e32 v0, 2, v0
	v_cndmask_b32_e32 v31, v215, v31, vcc
	v_cmp_lt_i32_e32 vcc, v214, v217
	v_lshlrev_b32_e32 v58, 2, v31
	v_lshl_add_u64 v[52:53], s[36:37], 0, v[32:33]
	v_cndmask_b32_e32 v31, v215, v214, vcc
	v_cmp_lt_i32_e32 vcc, v229, v217
	v_lshlrev_b32_e32 v59, 2, v31
	s_lshl_b64 s[18:19], s[8:9], 11
	v_cndmask_b32_e32 v31, v215, v229, vcc
	v_lshlrev_b32_e32 v60, 2, v31
	v_ashrrev_i32_e32 v31, 31, v30
	v_lshlrev_b64 v[30:31], 12, v[30:31]
	v_lshl_or_b32 v30, v38, 4, v30
	v_lshl_add_u64 v[54:55], s[56:57], 0, v[30:31]
	s_lshl_b64 s[24:25], s[8:9], 12
	s_mov_b64 s[30:31], 0
	v_readlane_b32 s60, v253, 42
	v_readlane_b32 s61, v253, 43
	v_readlane_b32 s62, v253, 44
	v_readlane_b32 s63, v253, 45
	v_readlane_b32 s64, v253, 46
	v_readlane_b32 s65, v253, 47
	v_readlane_b32 s66, v253, 48
	v_readlane_b32 s67, v253, 49
	v_readlane_b32 s68, v253, 50
	v_readlane_b32 s69, v253, 51
	v_readlane_b32 s70, v253, 52
	v_readlane_b32 s71, v253, 53
	s_branch .LBB0_495

; __device__ __forceinline__ unsigned xb_ld(unsigned* p)              { return __hip_atomic_load(p, __ATOMIC_RELAXED, __HIP_MEMORY_SCOPE_AGENT); }
; __device__ __forceinline__ unsigned xb_add(unsigned* p, unsigned v) { return __hip_atomic_fetch_add(p, v, __ATOMIC_RELAXED, __HIP_MEMORY_SCOPE_AGENT); }
; #define XB_SPIN(cond, bar) do { unsigned _sp = 0; while (cond) { __builtin_amdgcn_s_sleep(1); \
;     if ((++_sp & 255u) == 0u) { if (xb_ld(&(bar)[XB_TMO])) break; if (_sp > XB_SPIN_CAP) { atomicAdd(&(bar)[XB_TMO], 1u); break; } } } } while (0)
; __device__ __forceinline__ void xcd_barrier(const XcdBarrier& b) {
;     asm volatile("s_waitcnt vmcnt(0)" ::: "memory");
;     __syncthreads();
;     if (threadIdx.x == 0) {
;         unsigned* bar = b.bar;
;         __builtin_amdgcn_s_waitcnt(0);
;         unsigned nloc = b.st[0], nx = b.st[1];
;         if (nloc == 0u) { xcd_barrier_complete(bar, b.x, nloc, nx); b.st[0] = nloc; b.st[1] = nx; }
;         const unsigned old = xb_add(&bar[XB_XSUB(b.x)], 1u);
;         const unsigned gen = old / nloc;
;         if (old + 1u == (gen + 1u) * nloc) {
;             __builtin_amdgcn_fence(__ATOMIC_RELEASE, "agent");
;             asm volatile("s_waitcnt vmcnt(0)" ::: "memory");
;             const unsigned og = xb_add(&bar[XB_TOP], 1u);
;             const unsigned tg = og / nx;
;             if (og + 1u == (tg + 1u) * nx) xb_add(&bar[XB_TOPGEN], 1u);
;             else XB_SPIN(xb_ld(&bar[XB_TOPGEN]) == tg, bar);
;             __builtin_amdgcn_fence(__ATOMIC_ACQUIRE, "agent");
;             xb_add(&bar[XB_XGEN(b.x)], 1u);
;             asm volatile("s_waitcnt vmcnt(0)" ::: "memory");
;         } else {
;             XB_SPIN(xb_ld(&bar[XB_XGEN(b.x)]) == gen, bar);
;             __builtin_amdgcn_fence(__ATOMIC_ACQUIRE, "agent");
;             asm volatile("s_waitcnt vmcnt(0)" ::: "memory");
;         }
;     }
;     __syncthreads();
; }
; __global__ void __launch_bounds__(256, 2) hybrid_megakernel(Params p, int ph_lo, int ph_hi) {
;     ...
;   for (int ph = ph_lo; ph < ph_hi; ++ph) {
;     if (ph == 1) continue;
;     run_phase(p, ph, smem);
;     if (ph + 1 < ph_hi) {
;       if (ph_hi > 1000) cg::this_grid().sync();
;       xcd_barrier(xb);
;     }
.LBB0_498:
	s_add_i32 s12, s52, 1
	s_cmp_ge_i32 s12, s53
	s_cbranch_scc1 .LBB0_9
	s_cmp_lg_u32 s52, 0
	s_cbranch_scc1 .Llb_later
	v_writelane_b32 v255, s87, 60
	s_getreg_b32 s0, hwreg(HW_REG_XCC_ID, 0, 4)
	s_lshl_b32 s0, 1, s0
	v_readlane_b32 s1, v253, 0
	s_and_b32 s1, s1, 7
	s_lshl_b32 s1, s1, 2
	s_add_u32 s8, s88, 0x3fc0
	s_addc_u32 s9, s89, 0
	s_add_u32 s8, s8, s1
	s_addc_u32 s9, s9, 0
	v_cmp_eq_u32_e32 vcc, 0, v210
	s_and_saveexec_b64 s[6:7], vcc
	v_mov_b32_e32 v0, s0
	global_atomic_or v1, v0, s[8:9]
	s_mov_b64 exec, s[6:7]
	s_branch .Llb_global
.Llb_later:
	v_readlane_b32 s0, v255, 60
	s_cmp_lg_u32 s0, 0
	s_cbranch_scc1 .Llb_have
	s_add_u32 s8, s88, 0x3fc0
	s_addc_u32 s9, s89, 0
	global_load_dwordx4 v[2:5], v1, s[8:9] sc1
	global_load_dwordx4 v[6:9], v1, s[8:9] offset:16 sc1
	v_readlane_b32 s6, v253, 3
	v_readlane_b32 s7, v253, 4
	s_load_dword s6, s[6:7], 0x0
	s_waitcnt vmcnt(0) lgkmcnt(0)
	s_mov_b32 s0, 2
	s_cmpk_lg_u32 s6, 0x200
	s_cbranch_scc1 .Llb_set
	v_readfirstlane_b32 s6, v2
	s_add_i32 s7, s6, -1
	s_and_b32 s7, s7, s6
	s_cbranch_scc1 .Llb_set
	s_cmp_eq_u32 s6, 0
	s_cbranch_scc1 .Llb_set
	v_readfirstlane_b32 s6, v3
	s_add_i32 s7, s6, -1
	s_and_b32 s7, s7, s6
	s_cbranch_scc1 .Llb_set
	s_cmp_eq_u32 s6, 0
	s_cbranch_scc1 .Llb_set
	v_readfirstlane_b32 s6, v4
	s_add_i32 s7, s6, -1
	s_and_b32 s7, s7, s6
	s_cbranch_scc1 .Llb_set
	s_cmp_eq_u32 s6, 0
	s_cbranch_scc1 .Llb_set
	v_readfirstlane_b32 s6, v5
	s_add_i32 s7, s6, -1
	s_and_b32 s7, s7, s6
	s_cbranch_scc1 .Llb_set
	s_cmp_eq_u32 s6, 0
	s_cbranch_scc1 .Llb_set
	v_readfirstlane_b32 s6, v6
	s_add_i32 s7, s6, -1
	s_and_b32 s7, s7, s6
	s_cbranch_scc1 .Llb_set
	s_cmp_eq_u32 s6, 0
	s_cbranch_scc1 .Llb_set
	v_readfirstlane_b32 s6, v7
	s_add_i32 s7, s6, -1
	s_and_b32 s7, s7, s6
	s_cbranch_scc1 .Llb_set
	s_cmp_eq_u32 s6, 0
	s_cbranch_scc1 .Llb_set
	v_readfirstlane_b32 s6, v8
	s_add_i32 s7, s6, -1
	s_and_b32 s7, s7, s6
	s_cbranch_scc1 .Llb_set
	s_cmp_eq_u32 s6, 0
	s_cbranch_scc1 .Llb_set
	v_readfirstlane_b32 s6, v9
	s_add_i32 s7, s6, -1
	s_and_b32 s7, s7, s6
	s_cbranch_scc1 .Llb_set
	s_cmp_eq_u32 s6, 0
	s_cbranch_scc1 .Llb_set
	s_mov_b32 s0, 1
.Llb_set:
	v_writelane_b32 v255, s0, 60
	v_readlane_b32 s6, v253, 0
	s_and_b32 s6, s6, 7
	s_lshl_b32 s6, s6, 7
	s_addk_i32 s6, 0x3800
	s_add_u32 s6, s88, s6
	s_addc_u32 s7, s89, 0
	v_writelane_b32 v255, s6, 58
	v_writelane_b32 v255, s7, 59
.Llb_have:
	s_cmp_lg_u32 s0, 1
	s_cbranch_scc1 .Llb_global
	s_lshr_b32 s1, 0x19ce70, s52
	s_bitcmp1_b32 s1, 0
	s_cbranch_scc0 .Llb_global
	s_waitcnt vmcnt(0) lgkmcnt(0)
	s_barrier
	v_cmp_eq_u32_e32 vcc, 0, v210
	s_and_saveexec_b64 s[0:1], vcc
	s_cbranch_execz .Llbar_x
	v_readlane_b32 s6, v255, 58
	v_readlane_b32 s7, v255, 59
	v_mov_b32_e32 v0, 1
	s_nop 3
	global_atomic_add v0, v1, v0, s[6:7] sc0
	s_waitcnt vmcnt(0)
	v_readfirstlane_b32 s8, v0
	s_lshr_b32 s9, s8, 6
	s_and_b32 s8, s8, 63
	s_cmp_lg_u32 s8, 63
	s_cbranch_scc1 .Llbar_poll
	v_mov_b32_e32 v0, 1
	global_atomic_add v1, v0, s[6:7] offset:1024
	s_branch .Llbar_acq
.Llbar_poll:
	s_mov_b32 s8, 0
.Llbar_p:
	s_sleep 1
	global_load_dword v0, v1, s[6:7] offset:1024 sc1
	s_waitcnt vmcnt(0)
	v_readfirstlane_b32 s18, v0
	s_cmp_gt_u32 s18, s9
	s_cbranch_scc1 .Llbar_acq
	s_add_i32 s8, s8, 1
	s_cmp_lt_u32 s8, 0x100000
	s_cbranch_scc1 .Llbar_p
.Llbar_acq:
	s_waitcnt vmcnt(0)
	buffer_inv sc1
	s_waitcnt vmcnt(0)
.Llbar_x:
	s_or_b64 exec, exec, s[0:1]
	s_barrier
	s_branch .LBB0_9
.Llb_global:
	v_readlane_b32 s0, v254, 20
	v_readlane_b32 s1, v254, 21
	s_andn2_b64 vcc, exec, s[0:1]
	s_cbranch_vccnz .LBB0_511
	s_barrier
	s_mov_b64 s[0:1], exec
	v_readlane_b32 s6, v255, 17
	v_readlane_b32 s7, v255, 18
	s_and_b64 s[6:7], s[0:1], s[6:7]
	s_mov_b64 exec, s[6:7]
	s_cbranch_execz .LBB0_510
	v_readlane_b32 s6, v253, 3
	v_readlane_b32 s7, v253, 4
	buffer_wbl2 sc1
	s_waitcnt vmcnt(0)
	s_load_dwordx2 s[6:7], s[6:7], 0x58
	s_mov_b64 s[8:9], exec
	v_mbcnt_lo_u32_b32 v2, s8, 0
	v_mbcnt_hi_u32_b32 v2, s9, v2
	v_cmp_eq_u32_e32 vcc, 0, v2
	s_waitcnt lgkmcnt(0)
	global_load_dword v0, v1, s[6:7] offset:40
	s_and_saveexec_b64 s[18:19], vcc
	s_cbranch_execz .LBB0_503
	s_bcnt1_i32_b64 s8, s[8:9]
	v_mov_b32_e32 v3, s8
	global_atomic_add v3, v1, v3, s[6:7] offset:32 sc0
